# v10 + epilogue de-serialisation: pool-GEMM scale vectors loaded once; split-K slab epilogues issue both column-half gate loads together with counted waits
# speedup vs baseline: 1.0100x; 1.0100x over previous
; __device__ __forceinline__ unsigned cvt_pk_bf16(float lo, float hi) { unsigned r; asm volatile("v_cvt_pk_bf16_f32 %0, %1, %2" : "=v"(r) : "v"(lo), "v"(hi)); return r; }
;     __device__ __forceinline__ void operator()(const f32x4 (&acc)[2][2][4][2], const Unit& u, int wr, int wc, int fr, int fq) const {
;     ...
;             for (int ai = 0; ai < 2; ++ai)
; #pragma unroll
;                 for (int m = 0; m < 4; ++m) {
;                     const int row = row0 + ai * HALF + m * 16;
;                     const float* gp = gate + (size_t)modrow_of(row) * NMOD + col0;
;                     bf16_t* op = (bf16_t*)((char*)X + SLAB_MINUS_X) + ((size_t)u.kp * MS + (row - MP)) * DM + col0;
; #pragma unroll
;                     for (int bj = 0; bj < 2; ++bj) {
;                         const f32x4 g0 = (*(const f32x4*)(gp + bj * HALF) + *(const f32x4*)(gp + MODSB_DELTA + bj * HALF)) * coef, g1 = (*(const f32x4*)(gp + bj * HALF + 4) + *(const f32x4*)(gp + MODSB_DELTA + bj * HALF + 4)) * coef;
;                         const f32x4 o0 = g0 * acc[ai][bj][m][0], o1 = g1 * acc[ai][bj][m][1];
;                         u32x4 w; w.x = cvt_pk_bf16(o0[0], o0[1]); w.y = cvt_pk_bf16(o0[2], o0[3]); w.z = cvt_pk_bf16(o1[0], o1[1]); w.w = cvt_pk_bf16(o1[2], o1[3]);
;                         *(u32x4*)(op + bj * HALF) = w;
;                     }
.LBB0_505:
	s_lshl_b32 s30, s75, 8
	s_nop 15
	s_nop 15
	s_add_i32 s30, s30, s62
	v_or_b32_e32 v2, s30, v183
	v_lshl_or_b32 v10, s80, 8, v186
	s_mov_b64 s[28:29], -1
	s_andn2_b64 vcc, exec, s[26:27]
	v_ashrrev_i32_e32 v11, 31, v10
	v_or_b32_e32 v8, 16, v2
	v_or_b32_e32 v6, 32, v2
	v_or_b32_e32 v4, 48, v2
	s_cbranch_vccnz .LBB0_508
	v_add_u32_e32 v16, 0xffffe000, v2
	s_ashr_i32 s25, s30, 11
	v_lshrrev_b32_e32 v3, 2, v16
	v_cmp_gt_i32_e32 vcc, s59, v2
	v_or_b32_e32 v5, 4, v3
	v_mov_b32_e32 v3, s25
	v_cndmask_b32_e32 v5, v5, v3, vcc
	v_mov_b64_e32 v[12:13], s[10:11]
	s_mov_b32 s25, s1
	v_mad_i64_i32 v[18:19], s[26:27], v5, s58, v[12:13]
	v_lshlrev_b64 v[14:15], 2, v[10:11]
	s_lshl_b64 s[24:25], s[24:25], 21
	v_lshl_add_u64 v[174:175], v[18:19], 0, v[14:15]
	v_ashrrev_i32_e32 v17, 31, v16
	s_add_u32 s24, s60, s24
	s_addc_u32 s25, s61, s25
	v_lshlrev_b64 v[16:17], 12, v[16:17]
	v_add_co_u32_e32 v178, vcc, s67, v174
	v_lshl_add_u64 v[18:19], s[24:25], 0, v[16:17]
	v_lshlrev_b64 v[16:17], 1, v[10:11]
	v_lshl_add_u64 v[30:31], v[174:175], 0, s[16:17]
	v_addc_co_u32_e32 v179, vcc, 0, v175, vcc
	v_lshl_add_u64 v[176:177], v[18:19], 0, v[16:17]
	global_load_dwordx4 v[18:21], v[174:175], off offset:16
	global_load_dwordx4 v[22:25], v[174:175], off
	global_load_dwordx4 v[26:29], v[178:179], off
	s_nop 0
	global_load_dwordx4 v[30:33], v[30:31], off offset:16
	global_load_dwordx4 v[230:233], v[174:175], off offset:528
	global_load_dwordx4 v[234:237], v[174:175], off offset:512
	global_load_dwordx4 v[238:241], v[178:179], off offset:512
	v_lshl_add_u64 v[246:247], v[174:175], 0, s[18:19]
	s_nop 0
	global_load_dwordx4 v[242:245], v[246:247], off offset:16
	v_cmp_gt_i32_e32 vcc, s59, v8
	s_addk_i32 s30, 0x80
	s_waitcnt vmcnt(4)
	v_pk_add_f32 v[24:25], v[24:25], v[28:29]
	v_pk_add_f32 v[20:21], v[20:21], v[32:33]
	v_pk_add_f32 v[18:19], v[18:19], v[30:31]
	v_pk_add_f32 v[22:23], v[22:23], v[26:27]
	v_pk_mul_f32 v[20:21], v[20:21], 0.5 op_sel_hi:[1,0]
	v_pk_mul_f32 v[18:19], v[18:19], 0.5 op_sel_hi:[1,0]
	v_pk_mul_f32 v[24:25], v[24:25], 0.5 op_sel_hi:[1,0]
	v_pk_mul_f32 v[22:23], v[22:23], 0.5 op_sel_hi:[1,0]
	v_pk_mul_f32 v[26:27], v[156:157], v[20:21]
	v_pk_mul_f32 v[20:21], v[154:155], v[18:19]
	v_pk_mul_f32 v[24:25], v[160:161], v[24:25]
	v_pk_mul_f32 v[22:23], v[158:159], v[22:23]
	v_lshl_add_u64 v[30:31], v[174:175], 0, s[18:19]
	v_cvt_pk_bf16_f32 v18, v22, v23
	v_cvt_pk_bf16_f32 v19, v24, v25
	v_cvt_pk_bf16_f32 v20, v20, v21
	v_cvt_pk_bf16_f32 v21, v26, v27
	global_store_dwordx4 v[176:177], v[18:21], off
	s_nop 1
	s_waitcnt vmcnt(1)
	v_pk_add_f32 v[22:23], v[234:235], v[238:239]
	v_pk_add_f32 v[20:21], v[232:233], v[244:245]
	v_pk_add_f32 v[18:19], v[230:231], v[242:243]
	v_pk_add_f32 v[24:25], v[236:237], v[240:241]
	v_pk_mul_f32 v[22:23], v[22:23], 0.5 op_sel_hi:[1,0]
	v_pk_mul_f32 v[20:21], v[20:21], 0.5 op_sel_hi:[1,0]
	v_pk_mul_f32 v[18:19], v[18:19], 0.5 op_sel_hi:[1,0]
	v_pk_mul_f32 v[24:25], v[24:25], 0.5 op_sel_hi:[1,0]
	v_pk_mul_f32 v[22:23], v[150:151], v[22:23]
	v_pk_mul_f32 v[26:27], v[148:149], v[20:21]
	v_pk_mul_f32 v[20:21], v[146:147], v[18:19]
	v_cvt_pk_bf16_f32 v18, v22, v23
	v_pk_mul_f32 v[24:25], v[152:153], v[24:25]
	s_nop 0
	v_cvt_pk_bf16_f32 v19, v24, v25
	v_cvt_pk_bf16_f32 v20, v20, v21
	v_cvt_pk_bf16_f32 v21, v26, v27
	global_store_dwordx4 v[176:177], v[18:21], off offset:256
	s_nop 1
	v_add_u32_e32 v18, 0xffffe010, v2
	v_lshrrev_b32_e32 v5, 2, v18
	v_add_u32_e32 v5, 4, v5
	v_cndmask_b32_e32 v5, v5, v3, vcc
	v_mad_i64_i32 v[20:21], s[26:27], v5, s58, v[12:13]
	v_lshl_add_u64 v[174:175], v[20:21], 0, v[14:15]
	v_ashrrev_i32_e32 v19, 31, v18
	v_lshlrev_b64 v[18:19], 12, v[18:19]
	v_add_co_u32_e32 v178, vcc, s67, v174
	v_lshl_add_u64 v[18:19], s[24:25], 0, v[18:19]
	v_lshl_add_u64 v[30:31], v[174:175], 0, s[16:17]
	v_addc_co_u32_e32 v179, vcc, 0, v175, vcc
	v_lshl_add_u64 v[176:177], v[18:19], 0, v[16:17]
	global_load_dwordx4 v[18:21], v[174:175], off offset:16
	global_load_dwordx4 v[22:25], v[174:175], off
	global_load_dwordx4 v[26:29], v[178:179], off
	s_nop 0
	global_load_dwordx4 v[30:33], v[30:31], off offset:16
	global_load_dwordx4 v[230:233], v[174:175], off offset:528
	global_load_dwordx4 v[234:237], v[174:175], off offset:512
	global_load_dwordx4 v[238:241], v[178:179], off offset:512
	v_lshl_add_u64 v[246:247], v[174:175], 0, s[18:19]
	s_nop 0
	global_load_dwordx4 v[242:245], v[246:247], off offset:16
	v_cmp_gt_i32_e32 vcc, s59, v6
	s_waitcnt vmcnt(4)
	v_pk_add_f32 v[24:25], v[24:25], v[28:29]
	v_pk_add_f32 v[20:21], v[20:21], v[32:33]
	v_pk_add_f32 v[18:19], v[18:19], v[30:31]
	v_pk_add_f32 v[22:23], v[22:23], v[26:27]
	v_pk_mul_f32 v[20:21], v[20:21], 0.5 op_sel_hi:[1,0]
	v_pk_mul_f32 v[18:19], v[18:19], 0.5 op_sel_hi:[1,0]
	v_pk_mul_f32 v[24:25], v[24:25], 0.5 op_sel_hi:[1,0]
	v_pk_mul_f32 v[22:23], v[22:23], 0.5 op_sel_hi:[1,0]
	v_pk_mul_f32 v[26:27], v[140:141], v[20:21]
	v_pk_mul_f32 v[20:21], v[138:139], v[18:19]
	v_pk_mul_f32 v[24:25], v[144:145], v[24:25]
	v_pk_mul_f32 v[22:23], v[142:143], v[22:23]
	v_lshl_add_u64 v[30:31], v[174:175], 0, s[18:19]
	v_cvt_pk_bf16_f32 v18, v22, v23
	v_cvt_pk_bf16_f32 v19, v24, v25
	v_cvt_pk_bf16_f32 v20, v20, v21
	v_cvt_pk_bf16_f32 v21, v26, v27
	global_store_dwordx4 v[176:177], v[18:21], off
	s_nop 1
	s_waitcnt vmcnt(1)
; __device__ __forceinline__ unsigned cvt_pk_bf16(float lo, float hi) { unsigned r; asm volatile("v_cvt_pk_bf16_f32 %0, %1, %2" : "=v"(r) : "v"(lo), "v"(hi)); return r; }
;     __device__ __forceinline__ void operator()(const f32x4 (&acc)[2][2][4][2], const Unit& u, int wr, int wc, int fr, int fq) const {
;     ...
;             for (int ai = 0; ai < 2; ++ai)
; #pragma unroll
;                 for (int m = 0; m < 4; ++m) {
;                     const int row = row0 + ai * HALF + m * 16;
;                     const float* gp = gate + (size_t)modrow_of(row) * NMOD + col0;
;                     bf16_t* op = (bf16_t*)((char*)X + SLAB_MINUS_X) + ((size_t)u.kp * MS + (row - MP)) * DM + col0;
; #pragma unroll
;                     for (int bj = 0; bj < 2; ++bj) {
;                         const f32x4 g0 = (*(const f32x4*)(gp + bj * HALF) + *(const f32x4*)(gp + MODSB_DELTA + bj * HALF)) * coef, g1 = (*(const f32x4*)(gp + bj * HALF + 4) + *(const f32x4*)(gp + MODSB_DELTA + bj * HALF + 4)) * coef;
;                         const f32x4 o0 = g0 * acc[ai][bj][m][0], o1 = g1 * acc[ai][bj][m][1];
;                         u32x4 w; w.x = cvt_pk_bf16(o0[0], o0[1]); w.y = cvt_pk_bf16(o0[2], o0[3]); w.z = cvt_pk_bf16(o1[0], o1[1]); w.w = cvt_pk_bf16(o1[2], o1[3]);
;                         *(u32x4*)(op + bj * HALF) = w;
;                     }
	v_pk_add_f32 v[22:23], v[234:235], v[238:239]
	v_pk_add_f32 v[20:21], v[232:233], v[244:245]
	v_pk_add_f32 v[18:19], v[230:231], v[242:243]
	v_pk_add_f32 v[24:25], v[236:237], v[240:241]
	v_pk_mul_f32 v[22:23], v[22:23], 0.5 op_sel_hi:[1,0]
	v_pk_mul_f32 v[20:21], v[20:21], 0.5 op_sel_hi:[1,0]
	v_pk_mul_f32 v[18:19], v[18:19], 0.5 op_sel_hi:[1,0]
	v_pk_mul_f32 v[24:25], v[24:25], 0.5 op_sel_hi:[1,0]
	v_pk_mul_f32 v[22:23], v[134:135], v[22:23]
	v_pk_mul_f32 v[26:27], v[132:133], v[20:21]
	v_pk_mul_f32 v[20:21], v[130:131], v[18:19]
	v_cvt_pk_bf16_f32 v18, v22, v23
	v_pk_mul_f32 v[24:25], v[136:137], v[24:25]
	s_nop 0
	v_cvt_pk_bf16_f32 v19, v24, v25
	v_cvt_pk_bf16_f32 v20, v20, v21
	v_cvt_pk_bf16_f32 v21, v26, v27
	global_store_dwordx4 v[176:177], v[18:21], off offset:256
	s_nop 1
	v_add_u32_e32 v18, 0xffffe020, v2
	v_lshrrev_b32_e32 v5, 2, v18
	v_or_b32_e32 v5, 4, v5
	v_cndmask_b32_e32 v5, v5, v3, vcc
	v_mad_i64_i32 v[20:21], s[26:27], v5, s58, v[12:13]
	v_lshl_add_u64 v[32:33], v[20:21], 0, v[14:15]
	v_add_co_u32_e32 v178, vcc, s67, v32
	v_lshl_add_u64 v[174:175], v[32:33], 0, s[16:17]
	s_nop 0
	v_addc_co_u32_e32 v179, vcc, 0, v33, vcc
	global_load_dwordx4 v[20:23], v[32:33], off offset:16
	global_load_dwordx4 v[24:27], v[32:33], off
	global_load_dwordx4 v[28:31], v[178:179], off
	s_nop 0
	global_load_dwordx4 v[174:177], v[174:175], off offset:16
	global_load_dwordx4 v[230:233], v[32:33], off offset:528
	global_load_dwordx4 v[234:237], v[32:33], off offset:512
	global_load_dwordx4 v[238:241], v[178:179], off offset:512
	v_lshl_add_u64 v[246:247], v[32:33], 0, s[18:19]
	s_nop 0
	global_load_dwordx4 v[242:245], v[246:247], off offset:16
	v_ashrrev_i32_e32 v19, 31, v18
	v_lshlrev_b64 v[18:19], 12, v[18:19]
	v_lshl_add_u64 v[18:19], s[24:25], 0, v[18:19]
	v_lshl_add_u64 v[18:19], v[18:19], 0, v[16:17]
	v_cmp_gt_i32_e32 vcc, s59, v4
	s_waitcnt vmcnt(4)
	v_pk_add_f32 v[26:27], v[26:27], v[30:31]
	v_pk_add_f32 v[22:23], v[22:23], v[176:177]
	v_pk_add_f32 v[20:21], v[20:21], v[174:175]
	v_pk_add_f32 v[24:25], v[24:25], v[28:29]
	v_pk_mul_f32 v[22:23], v[22:23], 0.5 op_sel_hi:[1,0]
	v_pk_mul_f32 v[20:21], v[20:21], 0.5 op_sel_hi:[1,0]
	v_pk_mul_f32 v[26:27], v[26:27], 0.5 op_sel_hi:[1,0]
	v_pk_mul_f32 v[24:25], v[24:25], 0.5 op_sel_hi:[1,0]
	v_pk_mul_f32 v[28:29], v[124:125], v[22:23]
	v_pk_mul_f32 v[22:23], v[122:123], v[20:21]
	v_pk_mul_f32 v[26:27], v[128:129], v[26:27]
	v_pk_mul_f32 v[24:25], v[126:127], v[24:25]
	s_nop 0
	v_cvt_pk_bf16_f32 v20, v24, v25
	v_cvt_pk_bf16_f32 v21, v26, v27
	v_cvt_pk_bf16_f32 v22, v22, v23
	v_cvt_pk_bf16_f32 v23, v28, v29
	global_store_dwordx4 v[18:19], v[20:23], off
	v_lshl_add_u64 v[32:33], v[32:33], 0, s[18:19]
	s_nop 1
	s_waitcnt vmcnt(1)
	v_pk_add_f32 v[26:27], v[236:237], v[240:241]
	v_pk_add_f32 v[22:23], v[232:233], v[244:245]
	v_pk_add_f32 v[20:21], v[230:231], v[242:243]
	v_pk_add_f32 v[24:25], v[234:235], v[238:239]
	v_pk_mul_f32 v[22:23], v[22:23], 0.5 op_sel_hi:[1,0]
	v_pk_mul_f32 v[20:21], v[20:21], 0.5 op_sel_hi:[1,0]
	v_pk_mul_f32 v[26:27], v[26:27], 0.5 op_sel_hi:[1,0]
	v_pk_mul_f32 v[24:25], v[24:25], 0.5 op_sel_hi:[1,0]
	v_pk_mul_f32 v[28:29], v[116:117], v[22:23]
	v_pk_mul_f32 v[22:23], v[114:115], v[20:21]
	v_pk_mul_f32 v[26:27], v[120:121], v[26:27]
	v_pk_mul_f32 v[24:25], v[118:119], v[24:25]
	s_nop 0
	v_cvt_pk_bf16_f32 v20, v24, v25
	v_cvt_pk_bf16_f32 v21, v26, v27
	v_cvt_pk_bf16_f32 v22, v22, v23
	v_cvt_pk_bf16_f32 v23, v28, v29
	global_store_dwordx4 v[18:19], v[20:23], off offset:256
	v_add_u32_e32 v18, 0xffffe030, v2
	v_lshrrev_b32_e32 v5, 2, v18
	v_add_u32_e32 v5, 4, v5
	v_cndmask_b32_e32 v3, v5, v3, vcc
	v_mad_i64_i32 v[20:21], s[26:27], v3, s58, v[12:13]
	v_lshl_add_u64 v[174:175], v[20:21], 0, v[14:15]
	v_ashrrev_i32_e32 v19, 31, v18
	v_lshlrev_b64 v[18:19], 12, v[18:19]
	v_add_co_u32_e32 v178, vcc, s67, v174
	v_lshl_add_u64 v[18:19], s[24:25], 0, v[18:19]
	v_lshl_add_u64 v[30:31], v[174:175], 0, s[16:17]
	v_addc_co_u32_e32 v179, vcc, 0, v175, vcc
	v_lshl_add_u64 v[176:177], v[18:19], 0, v[16:17]
	global_load_dwordx4 v[18:21], v[174:175], off offset:16
	global_load_dwordx4 v[22:25], v[174:175], off
	global_load_dwordx4 v[26:29], v[178:179], off
	s_nop 0
	global_load_dwordx4 v[30:33], v[30:31], off offset:16
	global_load_dwordx4 v[230:233], v[174:175], off offset:528
	global_load_dwordx4 v[234:237], v[174:175], off offset:512
	global_load_dwordx4 v[238:241], v[178:179], off offset:512
	v_lshl_add_u64 v[246:247], v[174:175], 0, s[18:19]
	s_nop 0
	global_load_dwordx4 v[242:245], v[246:247], off offset:16
	s_ashr_i32 s26, s30, 11
	s_movk_i32 s27, 0x1f80
	v_cmp_gt_i32_e32 vcc, s27, v2
	s_waitcnt vmcnt(4)
	v_pk_add_f32 v[24:25], v[24:25], v[28:29]
	v_pk_add_f32 v[20:21], v[20:21], v[32:33]
	v_pk_add_f32 v[18:19], v[18:19], v[30:31]
	v_pk_add_f32 v[22:23], v[22:23], v[26:27]
	v_pk_mul_f32 v[20:21], v[20:21], 0.5 op_sel_hi:[1,0]
	v_pk_mul_f32 v[18:19], v[18:19], 0.5 op_sel_hi:[1,0]
	v_pk_mul_f32 v[24:25], v[24:25], 0.5 op_sel_hi:[1,0]
	v_pk_mul_f32 v[22:23], v[22:23], 0.5 op_sel_hi:[1,0]
	v_pk_mul_f32 v[26:27], v[108:109], v[20:21]
	v_pk_mul_f32 v[20:21], v[106:107], v[18:19]
	v_pk_mul_f32 v[24:25], v[112:113], v[24:25]
	v_pk_mul_f32 v[22:23], v[110:111], v[22:23]
	v_lshl_add_u64 v[30:31], v[174:175], 0, s[18:19]
	v_cvt_pk_bf16_f32 v18, v22, v23
	v_cvt_pk_bf16_f32 v19, v24, v25
	v_cvt_pk_bf16_f32 v20, v20, v21
	v_cvt_pk_bf16_f32 v21, v26, v27
	global_store_dwordx4 v[176:177], v[18:21], off
	s_nop 1
	s_waitcnt vmcnt(1)
; __device__ __forceinline__ unsigned cvt_pk_bf16(float lo, float hi) { unsigned r; asm volatile("v_cvt_pk_bf16_f32 %0, %1, %2" : "=v"(r) : "v"(lo), "v"(hi)); return r; }
;     __device__ __forceinline__ void operator()(const f32x4 (&acc)[2][2][4][2], const Unit& u, int wr, int wc, int fr, int fq) const {
;     ...
;             for (int ai = 0; ai < 2; ++ai)
; #pragma unroll
;                 for (int m = 0; m < 4; ++m) {
;                     const int row = row0 + ai * HALF + m * 16;
;                     const float* gp = gate + (size_t)modrow_of(row) * NMOD + col0;
;                     bf16_t* op = (bf16_t*)((char*)X + SLAB_MINUS_X) + ((size_t)u.kp * MS + (row - MP)) * DM + col0;
; #pragma unroll
;                     for (int bj = 0; bj < 2; ++bj) {
;                         const f32x4 g0 = (*(const f32x4*)(gp + bj * HALF) + *(const f32x4*)(gp + MODSB_DELTA + bj * HALF)) * coef, g1 = (*(const f32x4*)(gp + bj * HALF + 4) + *(const f32x4*)(gp + MODSB_DELTA + bj * HALF + 4)) * coef;
;                         const f32x4 o0 = g0 * acc[ai][bj][m][0], o1 = g1 * acc[ai][bj][m][1];
;                         u32x4 w; w.x = cvt_pk_bf16(o0[0], o0[1]); w.y = cvt_pk_bf16(o0[2], o0[3]); w.z = cvt_pk_bf16(o1[0], o1[1]); w.w = cvt_pk_bf16(o1[2], o1[3]);
;                         *(u32x4*)(op + bj * HALF) = w;
;                     }
	v_pk_add_f32 v[22:23], v[234:235], v[238:239]
	v_pk_add_f32 v[20:21], v[232:233], v[244:245]
	v_pk_add_f32 v[18:19], v[230:231], v[242:243]
	v_pk_add_f32 v[24:25], v[236:237], v[240:241]
	v_pk_mul_f32 v[22:23], v[22:23], 0.5 op_sel_hi:[1,0]
	v_pk_mul_f32 v[20:21], v[20:21], 0.5 op_sel_hi:[1,0]
	v_pk_mul_f32 v[18:19], v[18:19], 0.5 op_sel_hi:[1,0]
	v_pk_mul_f32 v[24:25], v[24:25], 0.5 op_sel_hi:[1,0]
	v_pk_mul_f32 v[22:23], v[102:103], v[22:23]
	v_pk_mul_f32 v[26:27], v[100:101], v[20:21]
	v_pk_mul_f32 v[20:21], v[98:99], v[18:19]
	v_cvt_pk_bf16_f32 v18, v22, v23
	v_pk_mul_f32 v[24:25], v[104:105], v[24:25]
	s_nop 0
	v_cvt_pk_bf16_f32 v19, v24, v25
	v_cvt_pk_bf16_f32 v20, v20, v21
	v_cvt_pk_bf16_f32 v21, v26, v27
	global_store_dwordx4 v[176:177], v[18:21], off offset:256
	s_nop 1
	v_add_u32_e32 v18, 0xffffe080, v2
	v_lshrrev_b32_e32 v3, 2, v18
	v_or_b32_e32 v5, 4, v3
	v_mov_b32_e32 v3, s26
	v_cndmask_b32_e32 v5, v5, v3, vcc
	v_mad_i64_i32 v[20:21], s[26:27], v5, s58, v[12:13]
	v_lshl_add_u64 v[32:33], v[20:21], 0, v[14:15]
	v_add_co_u32_e32 v178, vcc, s67, v32
	v_lshl_add_u64 v[174:175], v[32:33], 0, s[16:17]
	s_nop 0
	v_addc_co_u32_e32 v179, vcc, 0, v33, vcc
	global_load_dwordx4 v[20:23], v[32:33], off offset:16
	global_load_dwordx4 v[24:27], v[32:33], off
	global_load_dwordx4 v[28:31], v[178:179], off
	s_nop 0
	global_load_dwordx4 v[174:177], v[174:175], off offset:16
	global_load_dwordx4 v[230:233], v[32:33], off offset:528
	global_load_dwordx4 v[234:237], v[32:33], off offset:512
	global_load_dwordx4 v[238:241], v[178:179], off offset:512
	v_lshl_add_u64 v[246:247], v[32:33], 0, s[18:19]
	s_nop 0
	global_load_dwordx4 v[242:245], v[246:247], off offset:16
	v_ashrrev_i32_e32 v19, 31, v18
	v_lshlrev_b64 v[18:19], 12, v[18:19]
	v_lshl_add_u64 v[18:19], s[24:25], 0, v[18:19]
	v_lshl_add_u64 v[18:19], v[18:19], 0, v[16:17]
	s_movk_i32 s26, 0x1f70
	v_cmp_gt_i32_e32 vcc, s26, v2
	s_waitcnt vmcnt(4)
	v_pk_add_f32 v[26:27], v[26:27], v[30:31]
	v_pk_add_f32 v[22:23], v[22:23], v[176:177]
	v_pk_add_f32 v[20:21], v[20:21], v[174:175]
	v_pk_add_f32 v[24:25], v[24:25], v[28:29]
	v_pk_mul_f32 v[22:23], v[22:23], 0.5 op_sel_hi:[1,0]
	v_pk_mul_f32 v[20:21], v[20:21], 0.5 op_sel_hi:[1,0]
	v_pk_mul_f32 v[26:27], v[26:27], 0.5 op_sel_hi:[1,0]
	v_pk_mul_f32 v[24:25], v[24:25], 0.5 op_sel_hi:[1,0]
	v_pk_mul_f32 v[28:29], v[92:93], v[22:23]
	v_pk_mul_f32 v[22:23], v[90:91], v[20:21]
	v_pk_mul_f32 v[26:27], v[96:97], v[26:27]
	v_pk_mul_f32 v[24:25], v[94:95], v[24:25]
	s_nop 0
	v_cvt_pk_bf16_f32 v20, v24, v25
	v_cvt_pk_bf16_f32 v21, v26, v27
	v_cvt_pk_bf16_f32 v22, v22, v23
	v_cvt_pk_bf16_f32 v23, v28, v29
	global_store_dwordx4 v[18:19], v[20:23], off
	v_lshl_add_u64 v[32:33], v[32:33], 0, s[18:19]
	s_nop 1
	s_waitcnt vmcnt(1)
	v_pk_add_f32 v[26:27], v[236:237], v[240:241]
	v_pk_add_f32 v[22:23], v[232:233], v[244:245]
	v_pk_add_f32 v[20:21], v[230:231], v[242:243]
	v_pk_add_f32 v[24:25], v[234:235], v[238:239]
	v_pk_mul_f32 v[22:23], v[22:23], 0.5 op_sel_hi:[1,0]
	v_pk_mul_f32 v[20:21], v[20:21], 0.5 op_sel_hi:[1,0]
	v_pk_mul_f32 v[26:27], v[26:27], 0.5 op_sel_hi:[1,0]
	v_pk_mul_f32 v[24:25], v[24:25], 0.5 op_sel_hi:[1,0]
	v_pk_mul_f32 v[28:29], v[84:85], v[22:23]
	v_pk_mul_f32 v[22:23], v[82:83], v[20:21]
	v_pk_mul_f32 v[26:27], v[88:89], v[26:27]
	v_pk_mul_f32 v[24:25], v[86:87], v[24:25]
	s_nop 0
	v_cvt_pk_bf16_f32 v20, v24, v25
	v_cvt_pk_bf16_f32 v21, v26, v27
	v_cvt_pk_bf16_f32 v22, v22, v23
	v_cvt_pk_bf16_f32 v23, v28, v29
	global_store_dwordx4 v[18:19], v[20:23], off offset:256
	v_add_u32_e32 v18, 0xffffe090, v2
	v_lshrrev_b32_e32 v5, 2, v18
	v_add_u32_e32 v5, 4, v5
	v_cndmask_b32_e32 v5, v5, v3, vcc
	v_mad_i64_i32 v[20:21], s[26:27], v5, s58, v[12:13]
	v_lshl_add_u64 v[174:175], v[20:21], 0, v[14:15]
	v_ashrrev_i32_e32 v19, 31, v18
	v_lshlrev_b64 v[18:19], 12, v[18:19]
	v_add_co_u32_e32 v178, vcc, s67, v174
	v_lshl_add_u64 v[18:19], s[24:25], 0, v[18:19]
	v_lshl_add_u64 v[30:31], v[174:175], 0, s[16:17]
	v_addc_co_u32_e32 v179, vcc, 0, v175, vcc
	v_lshl_add_u64 v[176:177], v[18:19], 0, v[16:17]
	global_load_dwordx4 v[18:21], v[174:175], off offset:16
	global_load_dwordx4 v[22:25], v[174:175], off
	global_load_dwordx4 v[26:29], v[178:179], off
	s_nop 0
	global_load_dwordx4 v[30:33], v[30:31], off offset:16
	global_load_dwordx4 v[230:233], v[174:175], off offset:528
	global_load_dwordx4 v[234:237], v[174:175], off offset:512
	global_load_dwordx4 v[238:241], v[178:179], off offset:512
	v_lshl_add_u64 v[246:247], v[174:175], 0, s[18:19]
	s_nop 0
	global_load_dwordx4 v[242:245], v[246:247], off offset:16
	s_movk_i32 s26, 0x1f60
	v_cmp_gt_i32_e32 vcc, s26, v2
	s_waitcnt vmcnt(4)
	v_pk_add_f32 v[24:25], v[24:25], v[28:29]
	v_pk_add_f32 v[20:21], v[20:21], v[32:33]
	v_pk_add_f32 v[18:19], v[18:19], v[30:31]
	v_pk_add_f32 v[22:23], v[22:23], v[26:27]
	v_pk_mul_f32 v[20:21], v[20:21], 0.5 op_sel_hi:[1,0]
	v_pk_mul_f32 v[18:19], v[18:19], 0.5 op_sel_hi:[1,0]
	v_pk_mul_f32 v[24:25], v[24:25], 0.5 op_sel_hi:[1,0]
	v_pk_mul_f32 v[22:23], v[22:23], 0.5 op_sel_hi:[1,0]
	v_pk_mul_f32 v[26:27], v[76:77], v[20:21]
	v_pk_mul_f32 v[20:21], v[74:75], v[18:19]
	v_pk_mul_f32 v[24:25], v[80:81], v[24:25]
	v_pk_mul_f32 v[22:23], v[78:79], v[22:23]
	v_lshl_add_u64 v[30:31], v[174:175], 0, s[18:19]
	v_cvt_pk_bf16_f32 v18, v22, v23
	v_cvt_pk_bf16_f32 v19, v24, v25
	v_cvt_pk_bf16_f32 v20, v20, v21
	v_cvt_pk_bf16_f32 v21, v26, v27
	global_store_dwordx4 v[176:177], v[18:21], off
	s_nop 1
	s_waitcnt vmcnt(1)
; __device__ __forceinline__ unsigned cvt_pk_bf16(float lo, float hi) { unsigned r; asm volatile("v_cvt_pk_bf16_f32 %0, %1, %2" : "=v"(r) : "v"(lo), "v"(hi)); return r; }
;     __device__ __forceinline__ void operator()(const f32x4 (&acc)[2][2][4][2], const Unit& u, int wr, int wc, int fr, int fq) const {
;     ...
;             for (int ai = 0; ai < 2; ++ai)
; #pragma unroll
;                 for (int m = 0; m < 4; ++m) {
;                     const int row = row0 + ai * HALF + m * 16;
;                     const float* gp = gate + (size_t)modrow_of(row) * NMOD + col0;
;                     bf16_t* op = (bf16_t*)((char*)X + SLAB_MINUS_X) + ((size_t)u.kp * MS + (row - MP)) * DM + col0;
; #pragma unroll
;                     for (int bj = 0; bj < 2; ++bj) {
;                         const f32x4 g0 = (*(const f32x4*)(gp + bj * HALF) + *(const f32x4*)(gp + MODSB_DELTA + bj * HALF)) * coef, g1 = (*(const f32x4*)(gp + bj * HALF + 4) + *(const f32x4*)(gp + MODSB_DELTA + bj * HALF + 4)) * coef;
;                         const f32x4 o0 = g0 * acc[ai][bj][m][0], o1 = g1 * acc[ai][bj][m][1];
;                         u32x4 w; w.x = cvt_pk_bf16(o0[0], o0[1]); w.y = cvt_pk_bf16(o0[2], o0[3]); w.z = cvt_pk_bf16(o1[0], o1[1]); w.w = cvt_pk_bf16(o1[2], o1[3]);
;                         *(u32x4*)(op + bj * HALF) = w;
;                     }
	v_pk_add_f32 v[22:23], v[234:235], v[238:239]
	v_pk_add_f32 v[20:21], v[232:233], v[244:245]
	v_pk_add_f32 v[18:19], v[230:231], v[242:243]
	v_pk_add_f32 v[24:25], v[236:237], v[240:241]
	v_pk_mul_f32 v[22:23], v[22:23], 0.5 op_sel_hi:[1,0]
	v_pk_mul_f32 v[20:21], v[20:21], 0.5 op_sel_hi:[1,0]
	v_pk_mul_f32 v[18:19], v[18:19], 0.5 op_sel_hi:[1,0]
	v_pk_mul_f32 v[24:25], v[24:25], 0.5 op_sel_hi:[1,0]
	v_pk_mul_f32 v[22:23], v[70:71], v[22:23]
	v_pk_mul_f32 v[26:27], v[68:69], v[20:21]
	v_pk_mul_f32 v[20:21], v[66:67], v[18:19]
	v_cvt_pk_bf16_f32 v18, v22, v23
	v_pk_mul_f32 v[24:25], v[72:73], v[24:25]
	s_nop 0
	v_cvt_pk_bf16_f32 v19, v24, v25
	v_cvt_pk_bf16_f32 v20, v20, v21
	v_cvt_pk_bf16_f32 v21, v26, v27
	global_store_dwordx4 v[176:177], v[18:21], off offset:256
	s_nop 1
	v_add_u32_e32 v18, 0xffffe0a0, v2
	v_lshrrev_b32_e32 v5, 2, v18
	v_or_b32_e32 v5, 4, v5
	v_cndmask_b32_e32 v5, v5, v3, vcc
	v_mad_i64_i32 v[20:21], s[26:27], v5, s58, v[12:13]
	v_lshl_add_u64 v[32:33], v[20:21], 0, v[14:15]
	v_add_co_u32_e32 v178, vcc, s67, v32
	v_lshl_add_u64 v[174:175], v[32:33], 0, s[16:17]
	s_nop 0
	v_addc_co_u32_e32 v179, vcc, 0, v33, vcc
	global_load_dwordx4 v[20:23], v[32:33], off offset:16
	global_load_dwordx4 v[24:27], v[32:33], off
	global_load_dwordx4 v[28:31], v[178:179], off
	s_nop 0
	global_load_dwordx4 v[174:177], v[174:175], off offset:16
	global_load_dwordx4 v[230:233], v[32:33], off offset:528
	global_load_dwordx4 v[234:237], v[32:33], off offset:512
	global_load_dwordx4 v[238:241], v[178:179], off offset:512
	v_lshl_add_u64 v[246:247], v[32:33], 0, s[18:19]
	s_nop 0
	global_load_dwordx4 v[242:245], v[246:247], off offset:16
	v_ashrrev_i32_e32 v19, 31, v18
	v_lshlrev_b64 v[18:19], 12, v[18:19]
	v_lshl_add_u64 v[18:19], s[24:25], 0, v[18:19]
	v_lshl_add_u64 v[18:19], v[18:19], 0, v[16:17]
	s_movk_i32 s26, 0x1f50
	v_cmp_gt_i32_e32 vcc, s26, v2
	s_waitcnt vmcnt(4)
	v_pk_add_f32 v[26:27], v[26:27], v[30:31]
	v_pk_add_f32 v[22:23], v[22:23], v[176:177]
	v_pk_add_f32 v[20:21], v[20:21], v[174:175]
	v_pk_add_f32 v[24:25], v[24:25], v[28:29]
	v_pk_mul_f32 v[22:23], v[22:23], 0.5 op_sel_hi:[1,0]
	v_pk_mul_f32 v[20:21], v[20:21], 0.5 op_sel_hi:[1,0]
	v_pk_mul_f32 v[26:27], v[26:27], 0.5 op_sel_hi:[1,0]
	v_pk_mul_f32 v[24:25], v[24:25], 0.5 op_sel_hi:[1,0]
	v_pk_mul_f32 v[28:29], v[60:61], v[22:23]
	v_pk_mul_f32 v[22:23], v[58:59], v[20:21]
	v_pk_mul_f32 v[26:27], v[64:65], v[26:27]
	v_pk_mul_f32 v[24:25], v[62:63], v[24:25]
	s_nop 0
	v_cvt_pk_bf16_f32 v20, v24, v25
	v_cvt_pk_bf16_f32 v21, v26, v27
	v_cvt_pk_bf16_f32 v22, v22, v23
	v_cvt_pk_bf16_f32 v23, v28, v29
	global_store_dwordx4 v[18:19], v[20:23], off
	v_lshl_add_u64 v[32:33], v[32:33], 0, s[18:19]
	s_nop 1
	s_waitcnt vmcnt(1)
	v_pk_add_f32 v[26:27], v[236:237], v[240:241]
	v_pk_add_f32 v[22:23], v[232:233], v[244:245]
	v_pk_add_f32 v[20:21], v[230:231], v[242:243]
	v_pk_add_f32 v[24:25], v[234:235], v[238:239]
	v_pk_mul_f32 v[22:23], v[22:23], 0.5 op_sel_hi:[1,0]
	v_pk_mul_f32 v[20:21], v[20:21], 0.5 op_sel_hi:[1,0]
	v_pk_mul_f32 v[26:27], v[26:27], 0.5 op_sel_hi:[1,0]
	v_pk_mul_f32 v[24:25], v[24:25], 0.5 op_sel_hi:[1,0]
	v_pk_mul_f32 v[28:29], v[52:53], v[22:23]
	v_pk_mul_f32 v[22:23], v[50:51], v[20:21]
	v_pk_mul_f32 v[26:27], v[56:57], v[26:27]
	v_pk_mul_f32 v[24:25], v[54:55], v[24:25]
	s_nop 0
	v_cvt_pk_bf16_f32 v20, v24, v25
	v_cvt_pk_bf16_f32 v21, v26, v27
	v_cvt_pk_bf16_f32 v22, v22, v23
	v_cvt_pk_bf16_f32 v23, v28, v29
	global_store_dwordx4 v[18:19], v[20:23], off offset:256
	v_add_u32_e32 v18, 0xffffe0b0, v2
	v_lshrrev_b32_e32 v5, 2, v18
	v_add_u32_e32 v5, 4, v5
	v_cndmask_b32_e32 v3, v5, v3, vcc
	v_mad_i64_i32 v[12:13], s[26:27], v3, s58, v[12:13]
	v_lshl_add_u64 v[30:31], v[12:13], 0, v[14:15]
	v_ashrrev_i32_e32 v19, 31, v18
	v_lshlrev_b64 v[12:13], 12, v[18:19]
	v_add_co_u32_e32 v32, vcc, s67, v30
	v_lshl_add_u64 v[12:13], s[24:25], 0, v[12:13]
	v_lshl_add_u64 v[26:27], v[30:31], 0, s[16:17]
	v_addc_co_u32_e32 v33, vcc, 0, v31, vcc
	v_lshl_add_u64 v[12:13], v[12:13], 0, v[16:17]
	global_load_dwordx4 v[14:17], v[30:31], off offset:16
	global_load_dwordx4 v[18:21], v[30:31], off
	global_load_dwordx4 v[22:25], v[32:33], off
	s_nop 0
	global_load_dwordx4 v[26:29], v[26:27], off offset:16
	global_load_dwordx4 v[230:233], v[30:31], off offset:528
	global_load_dwordx4 v[234:237], v[30:31], off offset:512
	global_load_dwordx4 v[238:241], v[32:33], off offset:512
	v_lshl_add_u64 v[246:247], v[30:31], 0, s[18:19]
	s_nop 0
	global_load_dwordx4 v[242:245], v[246:247], off offset:16
	s_waitcnt vmcnt(4)
	v_pk_add_f32 v[20:21], v[20:21], v[24:25]
	v_pk_add_f32 v[16:17], v[16:17], v[28:29]
	v_pk_add_f32 v[14:15], v[14:15], v[26:27]
	v_pk_add_f32 v[18:19], v[18:19], v[22:23]
	v_pk_mul_f32 v[16:17], v[16:17], 0.5 op_sel_hi:[1,0]
	v_pk_mul_f32 v[14:15], v[14:15], 0.5 op_sel_hi:[1,0]
	v_pk_mul_f32 v[20:21], v[20:21], 0.5 op_sel_hi:[1,0]
	v_pk_mul_f32 v[18:19], v[18:19], 0.5 op_sel_hi:[1,0]
	v_pk_mul_f32 v[22:23], v[44:45], v[16:17]
	v_pk_mul_f32 v[16:17], v[42:43], v[14:15]
	v_pk_mul_f32 v[20:21], v[48:49], v[20:21]
	v_pk_mul_f32 v[18:19], v[46:47], v[18:19]
	v_lshl_add_u64 v[26:27], v[30:31], 0, s[18:19]
	v_cvt_pk_bf16_f32 v14, v18, v19
	v_cvt_pk_bf16_f32 v15, v20, v21
	v_cvt_pk_bf16_f32 v16, v16, v17
	v_cvt_pk_bf16_f32 v17, v22, v23
	global_store_dwordx4 v[12:13], v[14:17], off
	s_nop 1
	s_waitcnt vmcnt(1)
	v_pk_add_f32 v[20:21], v[236:237], v[240:241]
	v_pk_add_f32 v[16:17], v[232:233], v[244:245]
	v_pk_add_f32 v[14:15], v[230:231], v[242:243]
	v_pk_add_f32 v[18:19], v[234:235], v[238:239]
	v_pk_mul_f32 v[16:17], v[16:17], 0.5 op_sel_hi:[1,0]
	v_pk_mul_f32 v[14:15], v[14:15], 0.5 op_sel_hi:[1,0]
	v_pk_mul_f32 v[20:21], v[20:21], 0.5 op_sel_hi:[1,0]
	v_pk_mul_f32 v[18:19], v[18:19], 0.5 op_sel_hi:[1,0]
	v_pk_mul_f32 v[22:23], v[36:37], v[16:17]
	v_pk_mul_f32 v[16:17], v[34:35], v[14:15]
	v_pk_mul_f32 v[20:21], v[40:41], v[20:21]
	v_pk_mul_f32 v[18:19], v[38:39], v[18:19]
	s_nop 0
	v_cvt_pk_bf16_f32 v14, v18, v19
	v_cvt_pk_bf16_f32 v15, v20, v21
	v_cvt_pk_bf16_f32 v16, v16, v17
	v_cvt_pk_bf16_f32 v17, v22, v23
	global_store_dwordx4 v[12:13], v[14:17], off offset:256
	s_cbranch_execz .LBB0_509

;     __device__ __forceinline__ void operator()(const f32x4 (&acc)[2][2][4][2], const Unit& u, int wr, int wc, int fr, int fq) const {
;     ...
; #pragma unroll
;         for (int ai = 0; ai < 2; ++ai)
; #pragma unroll
;             for (int m = 0; m < 4; ++m) {
;                 unsigned char* rowp = MIX + (size_t)(row0 + ai * HALF + m * 16) * DM + col0;
; #pragma unroll
;                 for (int bj = 0; bj < 2; ++bj) { const f32x4 v0 = acc[ai][bj][m][0] * *(const f32x4*)(pscale + col0 + bj * HALF), v1 = acc[ai][bj][m][1] * *(const f32x4*)(pscale + col0 + bj * HALF + 4); u32x2 w;
;                     w.x = pk4_fp8(v0[0], v0[1], v0[2], v0[3]); w.y = pk4_fp8(v1[0], v1[1], v1[2], v1[3]);
;                     *(u32x2*)(rowp + bj * HALF) = w; }
;             }
.LBB0_1009:
	v_lshl_or_b32 v144, s66, 8, v149
	v_readlane_b32 s68, v253, 6
	v_ashrrev_i32_e32 v145, 31, v144
	v_readlane_b32 s82, v253, 20
	v_readlane_b32 s83, v253, 21
	v_mov_b32_e32 v162, 0
	v_mov_b32_e32 v163, 0
	v_lshl_add_u64 v[142:143], v[144:145], 2, s[82:83]
	global_load_dwordx4 v[230:233], v[142:143], off
	global_load_dwordx4 v[234:237], v[142:143], off offset:16
	global_load_dwordx4 v[238:241], v[142:143], off offset:512
	global_load_dwordx4 v[242:245], v[142:143], off offset:528
	v_lshl_add_u32 v146, s24, 8, v1
	v_ashrrev_i32_e32 v147, 31, v146
	s_mov_b32 s17, 0x40000
	s_mov_b64 s[26:27], 0x40000
	v_readlane_b32 s69, v253, 7
	v_readlane_b32 s70, v253, 8
	v_readlane_b32 s71, v253, 9
	v_readlane_b32 s72, v253, 10
	v_readlane_b32 s73, v253, 11
	v_readlane_b32 s74, v253, 12
	v_readlane_b32 s75, v253, 13
	v_readlane_b32 s76, v253, 14
	v_readlane_b32 s77, v253, 15
	v_readlane_b32 s78, v253, 16
	v_readlane_b32 s79, v253, 17
	v_readlane_b32 s80, v253, 18
	v_readlane_b32 s81, v253, 19
	s_waitcnt vmcnt(0)
	v_pk_mul_f32 v[122:123], v[122:123], v[230:231]
	v_pk_mul_f32 v[126:127], v[126:127], v[234:235]
	v_med3_f32 v122, v122, s64, v153
	v_med3_f32 v123, v123, s64, v153
	v_med3_f32 v126, v126, s64, v153
	v_med3_f32 v127, v127, s64, v153
	v_cvt_pk_fp8_f32 v162, v122, v123
	v_cvt_pk_fp8_f32 v163, v126, v127
	v_pk_mul_f32 v[124:125], v[124:125], v[232:233]
	v_pk_mul_f32 v[128:129], v[128:129], v[236:237]
	v_med3_f32 v124, v124, s64, v153
	v_med3_f32 v125, v125, s64, v153
	v_med3_f32 v122, v128, s64, v153
	v_med3_f32 v123, v129, s64, v153
	v_cvt_pk_fp8_f32 v162, v124, v125 op_sel:[0,0,1]
	v_cvt_pk_fp8_f32 v163, v122, v123 op_sel:[0,0,1]
	v_lshlrev_b64 v[122:123], 11, v[146:147]
	v_lshl_add_u64 v[122:123], s[4:5], 0, v[122:123]
	v_lshl_add_u64 v[122:123], v[122:123], 0, v[144:145]
	global_store_dwordx2 v[122:123], v[162:163], off
	v_mov_b32_e32 v128, 0
	v_mov_b32_e32 v129, 0
	v_pk_mul_f32 v[114:115], v[114:115], v[238:239]
	v_pk_mul_f32 v[118:119], v[118:119], v[242:243]
	v_med3_f32 v114, v114, s64, v153
	v_med3_f32 v115, v115, s64, v153
	v_med3_f32 v118, v118, s64, v153
	v_med3_f32 v119, v119, s64, v153
	v_cvt_pk_fp8_f32 v128, v114, v115
	v_cvt_pk_fp8_f32 v129, v118, v119
	v_pk_mul_f32 v[116:117], v[116:117], v[240:241]
	v_pk_mul_f32 v[120:121], v[120:121], v[244:245]
	v_med3_f32 v116, v116, s64, v153
	v_med3_f32 v117, v117, s64, v153
	v_med3_f32 v114, v120, s64, v153
	v_med3_f32 v115, v121, s64, v153
	v_cvt_pk_fp8_f32 v128, v116, v117 op_sel:[0,0,1]
	v_cvt_pk_fp8_f32 v129, v114, v115 op_sel:[0,0,1]
	v_mov_b32_e32 v124, 0
	v_mov_b32_e32 v125, 0
	v_or_b32_e32 v126, 16, v146
	global_store_dwordx2 v[122:123], v[128:129], off offset:128
	v_ashrrev_i32_e32 v127, 31, v126
	v_pk_mul_f32 v[106:107], v[106:107], v[230:231]
	v_pk_mul_f32 v[110:111], v[110:111], v[234:235]
	v_med3_f32 v106, v106, s64, v153
	v_med3_f32 v107, v107, s64, v153
	v_med3_f32 v110, v110, s64, v153
	v_med3_f32 v111, v111, s64, v153
	v_cvt_pk_fp8_f32 v124, v106, v107
	v_cvt_pk_fp8_f32 v125, v110, v111
	v_pk_mul_f32 v[108:109], v[108:109], v[232:233]
	v_pk_mul_f32 v[112:113], v[112:113], v[236:237]
	v_med3_f32 v108, v108, s64, v153
	v_med3_f32 v109, v109, s64, v153
	v_med3_f32 v106, v112, s64, v153
	v_med3_f32 v107, v113, s64, v153
	v_cvt_pk_fp8_f32 v124, v108, v109 op_sel:[0,0,1]
	v_cvt_pk_fp8_f32 v125, v106, v107 op_sel:[0,0,1]
	v_lshlrev_b64 v[106:107], 11, v[126:127]
	v_lshl_add_u64 v[106:107], s[4:5], 0, v[106:107]
	v_lshl_add_u64 v[114:115], v[106:107], 0, v[144:145]
	global_store_dwordx2 v[114:115], v[124:125], off
	v_mov_b32_e32 v116, 0
	v_mov_b32_e32 v117, 0
	v_pk_mul_f32 v[98:99], v[98:99], v[238:239]
	v_pk_mul_f32 v[102:103], v[102:103], v[242:243]
	v_med3_f32 v98, v98, s64, v153
	v_med3_f32 v99, v99, s64, v153
	v_med3_f32 v102, v102, s64, v153
	v_med3_f32 v103, v103, s64, v153
	v_cvt_pk_fp8_f32 v116, v98, v99
	v_cvt_pk_fp8_f32 v117, v102, v103
	v_pk_mul_f32 v[100:101], v[100:101], v[240:241]
	v_pk_mul_f32 v[104:105], v[104:105], v[244:245]
	v_med3_f32 v100, v100, s64, v153
	v_med3_f32 v101, v101, s64, v153
	v_med3_f32 v98, v104, s64, v153
	v_med3_f32 v99, v105, s64, v153
	v_cvt_pk_fp8_f32 v116, v100, v101 op_sel:[0,0,1]
	v_cvt_pk_fp8_f32 v117, v98, v99 op_sel:[0,0,1]
	v_mov_b32_e32 v106, 0
	v_mov_b32_e32 v107, 0
	v_or_b32_e32 v108, 32, v146
	global_store_dwordx2 v[114:115], v[116:117], off offset:128
	v_ashrrev_i32_e32 v109, 31, v108
	v_pk_mul_f32 v[90:91], v[90:91], v[230:231]
	v_pk_mul_f32 v[94:95], v[94:95], v[234:235]
	v_med3_f32 v90, v90, s64, v153
	v_med3_f32 v91, v91, s64, v153
	v_med3_f32 v94, v94, s64, v153
	v_med3_f32 v95, v95, s64, v153
	v_cvt_pk_fp8_f32 v106, v90, v91
	v_cvt_pk_fp8_f32 v107, v94, v95
	v_pk_mul_f32 v[92:93], v[92:93], v[232:233]
	v_pk_mul_f32 v[96:97], v[96:97], v[236:237]
	v_med3_f32 v92, v92, s64, v153
	v_med3_f32 v93, v93, s64, v153
	v_med3_f32 v90, v96, s64, v153
	v_med3_f32 v91, v97, s64, v153
	v_cvt_pk_fp8_f32 v106, v92, v93 op_sel:[0,0,1]
	v_cvt_pk_fp8_f32 v107, v90, v91 op_sel:[0,0,1]
	v_lshlrev_b64 v[90:91], 11, v[108:109]
	v_lshl_add_u64 v[90:91], s[4:5], 0, v[90:91]
	v_lshl_add_u64 v[98:99], v[90:91], 0, v[144:145]
	global_store_dwordx2 v[98:99], v[106:107], off
	v_mov_b32_e32 v100, 0
	v_mov_b32_e32 v101, 0
	v_pk_mul_f32 v[82:83], v[82:83], v[238:239]
	v_pk_mul_f32 v[86:87], v[86:87], v[242:243]
	v_med3_f32 v82, v82, s64, v153
	v_med3_f32 v83, v83, s64, v153
	v_med3_f32 v86, v86, s64, v153
	v_med3_f32 v87, v87, s64, v153
	v_cvt_pk_fp8_f32 v100, v82, v83
	v_cvt_pk_fp8_f32 v101, v86, v87
	v_pk_mul_f32 v[84:85], v[84:85], v[240:241]
	v_pk_mul_f32 v[88:89], v[88:89], v[244:245]
	v_med3_f32 v84, v84, s64, v153
	v_med3_f32 v85, v85, s64, v153
;     __device__ __forceinline__ void operator()(const f32x4 (&acc)[2][2][4][2], const Unit& u, int wr, int wc, int fr, int fq) const {
;     ...
; #pragma unroll
;         for (int ai = 0; ai < 2; ++ai)
; #pragma unroll
;             for (int m = 0; m < 4; ++m) {
;                 unsigned char* rowp = MIX + (size_t)(row0 + ai * HALF + m * 16) * DM + col0;
; #pragma unroll
;                 for (int bj = 0; bj < 2; ++bj) { const f32x4 v0 = acc[ai][bj][m][0] * *(const f32x4*)(pscale + col0 + bj * HALF), v1 = acc[ai][bj][m][1] * *(const f32x4*)(pscale + col0 + bj * HALF + 4); u32x2 w;
;                     w.x = pk4_fp8(v0[0], v0[1], v0[2], v0[3]); w.y = pk4_fp8(v1[0], v1[1], v1[2], v1[3]);
;                     *(u32x2*)(rowp + bj * HALF) = w; }
;             }
	v_med3_f32 v82, v88, s64, v153
	v_med3_f32 v83, v89, s64, v153
	v_cvt_pk_fp8_f32 v100, v84, v85 op_sel:[0,0,1]
	v_cvt_pk_fp8_f32 v101, v82, v83 op_sel:[0,0,1]
	v_mov_b32_e32 v90, 0
	v_mov_b32_e32 v91, 0
	v_or_b32_e32 v92, 48, v146
	global_store_dwordx2 v[98:99], v[100:101], off offset:128
	v_ashrrev_i32_e32 v93, 31, v92
	v_pk_mul_f32 v[74:75], v[74:75], v[230:231]
	v_pk_mul_f32 v[78:79], v[78:79], v[234:235]
	v_med3_f32 v74, v74, s64, v153
	v_med3_f32 v75, v75, s64, v153
	v_med3_f32 v78, v78, s64, v153
	v_med3_f32 v79, v79, s64, v153
	v_cvt_pk_fp8_f32 v90, v74, v75
	v_cvt_pk_fp8_f32 v91, v78, v79
	v_pk_mul_f32 v[76:77], v[76:77], v[232:233]
	v_pk_mul_f32 v[80:81], v[80:81], v[236:237]
	v_med3_f32 v76, v76, s64, v153
	v_med3_f32 v77, v77, s64, v153
	v_med3_f32 v74, v80, s64, v153
	v_med3_f32 v75, v81, s64, v153
	v_cvt_pk_fp8_f32 v90, v76, v77 op_sel:[0,0,1]
	v_cvt_pk_fp8_f32 v91, v74, v75 op_sel:[0,0,1]
	v_lshlrev_b64 v[74:75], 11, v[92:93]
	v_lshl_add_u64 v[74:75], s[4:5], 0, v[74:75]
	v_lshl_add_u64 v[82:83], v[74:75], 0, v[144:145]
	global_store_dwordx2 v[82:83], v[90:91], off
	v_mov_b32_e32 v84, 0
	v_mov_b32_e32 v85, 0
	v_pk_mul_f32 v[66:67], v[66:67], v[238:239]
	v_pk_mul_f32 v[70:71], v[70:71], v[242:243]
	v_med3_f32 v66, v66, s64, v153
	v_med3_f32 v67, v67, s64, v153
	v_med3_f32 v70, v70, s64, v153
	v_med3_f32 v71, v71, s64, v153
	v_cvt_pk_fp8_f32 v84, v66, v67
	v_cvt_pk_fp8_f32 v85, v70, v71
	v_pk_mul_f32 v[68:69], v[68:69], v[240:241]
	v_pk_mul_f32 v[72:73], v[72:73], v[244:245]
	v_med3_f32 v68, v68, s64, v153
	v_med3_f32 v69, v69, s64, v153
	v_med3_f32 v66, v72, s64, v153
	v_med3_f32 v67, v73, s64, v153
	v_cvt_pk_fp8_f32 v84, v68, v69 op_sel:[0,0,1]
	v_cvt_pk_fp8_f32 v85, v66, v67 op_sel:[0,0,1]
	v_mov_b32_e32 v74, 0
	v_mov_b32_e32 v75, 0
	global_store_dwordx2 v[82:83], v[84:85], off offset:128
	v_pk_mul_f32 v[58:59], v[58:59], v[230:231]
	v_pk_mul_f32 v[62:63], v[62:63], v[234:235]
	v_med3_f32 v58, v58, s64, v153
	v_med3_f32 v59, v59, s64, v153
	v_med3_f32 v62, v62, s64, v153
	v_med3_f32 v63, v63, s64, v153
	v_cvt_pk_fp8_f32 v74, v58, v59
	v_cvt_pk_fp8_f32 v75, v62, v63
	v_pk_mul_f32 v[60:61], v[60:61], v[232:233]
	v_pk_mul_f32 v[64:65], v[64:65], v[236:237]
	v_med3_f32 v60, v60, s64, v153
	v_med3_f32 v61, v61, s64, v153
	v_med3_f32 v58, v64, s64, v153
	v_med3_f32 v59, v65, s64, v153
	v_cvt_pk_fp8_f32 v74, v60, v61 op_sel:[0,0,1]
	v_cvt_pk_fp8_f32 v75, v58, v59 op_sel:[0,0,1]
	v_add_co_u32_e32 v58, vcc, s17, v122
	v_mov_b32_e32 v66, 0
	s_nop 0
	v_addc_co_u32_e32 v59, vcc, 0, v123, vcc
	global_store_dwordx2 v[58:59], v[74:75], off
	s_nop 0
	v_mov_b32_e32 v67, 0
	s_mov_b32 s17, 0x48000
	v_pk_mul_f32 v[50:51], v[50:51], v[238:239]
	v_pk_mul_f32 v[54:55], v[54:55], v[242:243]
	v_med3_f32 v50, v50, s64, v153
	v_med3_f32 v51, v51, s64, v153
	v_med3_f32 v54, v54, s64, v153
	v_med3_f32 v55, v55, s64, v153
	v_cvt_pk_fp8_f32 v66, v50, v51
	v_cvt_pk_fp8_f32 v67, v54, v55
	v_pk_mul_f32 v[52:53], v[52:53], v[240:241]
	v_pk_mul_f32 v[56:57], v[56:57], v[244:245]
	v_med3_f32 v52, v52, s64, v153
	v_med3_f32 v53, v53, s64, v153
	v_med3_f32 v50, v56, s64, v153
	v_med3_f32 v51, v57, s64, v153
	v_cvt_pk_fp8_f32 v66, v52, v53 op_sel:[0,0,1]
	v_cvt_pk_fp8_f32 v67, v50, v51 op_sel:[0,0,1]
	v_lshl_add_u64 v[50:51], v[122:123], 0, s[26:27]
	v_mov_b32_e32 v58, 0
	v_mov_b32_e32 v59, 0
	global_store_dwordx2 v[50:51], v[66:67], off offset:128
	s_nop 0
	s_mov_b64 s[26:27], 0x48000
	v_pk_mul_f32 v[42:43], v[42:43], v[230:231]
	v_pk_mul_f32 v[46:47], v[46:47], v[234:235]
	v_med3_f32 v42, v42, s64, v153
	v_med3_f32 v43, v43, s64, v153
	v_med3_f32 v46, v46, s64, v153
	v_med3_f32 v47, v47, s64, v153
	v_cvt_pk_fp8_f32 v58, v42, v43
	v_cvt_pk_fp8_f32 v59, v46, v47
	v_pk_mul_f32 v[44:45], v[44:45], v[232:233]
	v_pk_mul_f32 v[48:49], v[48:49], v[236:237]
	v_med3_f32 v44, v44, s64, v153
	v_med3_f32 v45, v45, s64, v153
	v_med3_f32 v42, v48, s64, v153
	v_med3_f32 v43, v49, s64, v153
	v_cvt_pk_fp8_f32 v58, v44, v45 op_sel:[0,0,1]
	v_cvt_pk_fp8_f32 v59, v42, v43 op_sel:[0,0,1]
	v_add_co_u32_e32 v42, vcc, s17, v122
	v_mov_b32_e32 v50, 0
	s_nop 0
;     __device__ __forceinline__ void operator()(const f32x4 (&acc)[2][2][4][2], const Unit& u, int wr, int wc, int fr, int fq) const {
;     ...
; #pragma unroll
;         for (int ai = 0; ai < 2; ++ai)
; #pragma unroll
;             for (int m = 0; m < 4; ++m) {
;                 unsigned char* rowp = MIX + (size_t)(row0 + ai * HALF + m * 16) * DM + col0;
; #pragma unroll
;                 for (int bj = 0; bj < 2; ++bj) { const f32x4 v0 = acc[ai][bj][m][0] * *(const f32x4*)(pscale + col0 + bj * HALF), v1 = acc[ai][bj][m][1] * *(const f32x4*)(pscale + col0 + bj * HALF + 4); u32x2 w;
;                     w.x = pk4_fp8(v0[0], v0[1], v0[2], v0[3]); w.y = pk4_fp8(v1[0], v1[1], v1[2], v1[3]);
;                     *(u32x2*)(rowp + bj * HALF) = w; }
;             }
	v_addc_co_u32_e32 v43, vcc, 0, v123, vcc
	global_store_dwordx2 v[42:43], v[58:59], off
	s_nop 0
	v_mov_b32_e32 v51, 0
	s_mov_b32 s17, 0x50000
	v_pk_mul_f32 v[34:35], v[34:35], v[238:239]
	v_pk_mul_f32 v[38:39], v[38:39], v[242:243]
	v_med3_f32 v34, v34, s64, v153
	v_med3_f32 v35, v35, s64, v153
	v_med3_f32 v38, v38, s64, v153
	v_med3_f32 v39, v39, s64, v153
	v_cvt_pk_fp8_f32 v50, v34, v35
	v_cvt_pk_fp8_f32 v51, v38, v39
	v_pk_mul_f32 v[36:37], v[36:37], v[240:241]
	v_pk_mul_f32 v[40:41], v[40:41], v[244:245]
	v_med3_f32 v36, v36, s64, v153
	v_med3_f32 v37, v37, s64, v153
	v_med3_f32 v34, v40, s64, v153
	v_med3_f32 v35, v41, s64, v153
	v_cvt_pk_fp8_f32 v50, v36, v37 op_sel:[0,0,1]
	v_cvt_pk_fp8_f32 v51, v34, v35 op_sel:[0,0,1]
	v_lshl_add_u64 v[34:35], v[122:123], 0, s[26:27]
	v_mov_b32_e32 v42, 0
	v_mov_b32_e32 v43, 0
	global_store_dwordx2 v[34:35], v[50:51], off offset:128
	s_nop 0
	s_mov_b64 s[26:27], 0x50000
	v_pk_mul_f32 v[26:27], v[26:27], v[230:231]
	v_pk_mul_f32 v[30:31], v[30:31], v[234:235]
	v_med3_f32 v26, v26, s64, v153
	v_med3_f32 v27, v27, s64, v153
	v_med3_f32 v30, v30, s64, v153
	v_med3_f32 v31, v31, s64, v153
	v_cvt_pk_fp8_f32 v42, v26, v27
	v_cvt_pk_fp8_f32 v43, v30, v31
	v_pk_mul_f32 v[28:29], v[28:29], v[232:233]
	v_pk_mul_f32 v[32:33], v[32:33], v[236:237]
	v_med3_f32 v28, v28, s64, v153
	v_med3_f32 v29, v29, s64, v153
	v_med3_f32 v26, v32, s64, v153
	v_med3_f32 v27, v33, s64, v153
	v_cvt_pk_fp8_f32 v42, v28, v29 op_sel:[0,0,1]
	v_cvt_pk_fp8_f32 v43, v26, v27 op_sel:[0,0,1]
	v_add_co_u32_e32 v26, vcc, s17, v122
	v_mov_b32_e32 v34, 0
	s_nop 0
	v_addc_co_u32_e32 v27, vcc, 0, v123, vcc
	global_store_dwordx2 v[26:27], v[42:43], off
	s_nop 0
	v_mov_b32_e32 v35, 0
	v_pk_mul_f32 v[18:19], v[18:19], v[238:239]
	v_pk_mul_f32 v[22:23], v[22:23], v[242:243]
	v_med3_f32 v18, v18, s64, v153
	v_med3_f32 v19, v19, s64, v153
	v_med3_f32 v22, v22, s64, v153
	v_med3_f32 v23, v23, s64, v153
	v_cvt_pk_fp8_f32 v34, v18, v19
	v_cvt_pk_fp8_f32 v35, v22, v23
	v_pk_mul_f32 v[20:21], v[20:21], v[240:241]
	v_pk_mul_f32 v[24:25], v[24:25], v[244:245]
	v_med3_f32 v20, v20, s64, v153
	v_med3_f32 v21, v21, s64, v153
	v_med3_f32 v18, v24, s64, v153
	v_med3_f32 v19, v25, s64, v153
	v_cvt_pk_fp8_f32 v34, v20, v21 op_sel:[0,0,1]
	v_cvt_pk_fp8_f32 v35, v18, v19 op_sel:[0,0,1]
	v_lshl_add_u64 v[18:19], v[122:123], 0, s[26:27]
	v_mov_b32_e32 v26, 0
	v_mov_b32_e32 v27, 0
	global_store_dwordx2 v[18:19], v[34:35], off offset:128
	s_nop 0
	s_mov_b64 s[26:27], 0x58000
	v_pk_mul_f32 v[10:11], v[10:11], v[230:231]
	v_pk_mul_f32 v[14:15], v[14:15], v[234:235]
	v_med3_f32 v10, v10, s64, v153
	v_med3_f32 v11, v11, s64, v153
	v_med3_f32 v14, v14, s64, v153
	v_med3_f32 v15, v15, s64, v153
	v_cvt_pk_fp8_f32 v26, v10, v11
	v_cvt_pk_fp8_f32 v27, v14, v15
	v_pk_mul_f32 v[12:13], v[12:13], v[232:233]
	v_pk_mul_f32 v[16:17], v[16:17], v[236:237]
	v_med3_f32 v12, v12, s64, v153
	v_med3_f32 v13, v13, s64, v153
	v_med3_f32 v10, v16, s64, v153
	v_med3_f32 v11, v17, s64, v153
	v_cvt_pk_fp8_f32 v26, v12, v13 op_sel:[0,0,1]
	v_cvt_pk_fp8_f32 v27, v10, v11 op_sel:[0,0,1]
	v_add_co_u32_e32 v10, vcc, s65, v122
	v_mov_b32_e32 v18, 0
	s_nop 0
	v_addc_co_u32_e32 v11, vcc, 0, v123, vcc
	global_store_dwordx2 v[10:11], v[26:27], off
	s_nop 0
	v_mov_b32_e32 v19, 0
	s_andn2_b64 vcc, exec, s[2:3]
	s_mov_b64 s[2:3], -1
	v_pk_mul_f32 v[2:3], v[2:3], v[238:239]
	v_pk_mul_f32 v[6:7], v[6:7], v[242:243]
	v_med3_f32 v2, v2, s64, v153
	v_med3_f32 v3, v3, s64, v153
	v_med3_f32 v6, v6, s64, v153
	v_med3_f32 v7, v7, s64, v153
	v_cvt_pk_fp8_f32 v18, v2, v3
	v_cvt_pk_fp8_f32 v19, v6, v7
	v_pk_mul_f32 v[4:5], v[4:5], v[240:241]
	v_pk_mul_f32 v[8:9], v[8:9], v[244:245]
	v_med3_f32 v4, v4, s64, v153
	v_med3_f32 v5, v5, s64, v153
	v_med3_f32 v2, v8, s64, v153
	v_med3_f32 v3, v9, s64, v153
	v_cvt_pk_fp8_f32 v18, v4, v5 op_sel:[0,0,1]
	v_cvt_pk_fp8_f32 v19, v2, v3 op_sel:[0,0,1]
	v_lshl_add_u64 v[2:3], v[122:123], 0, s[26:27]
	global_store_dwordx2 v[2:3], v[18:19], off offset:128
	s_cbranch_vccnz .LBB0_1004
	s_andn2_b64 vcc, exec, s[0:1]
	s_cbranch_vccnz .LBB0_1003
	s_barrier
	s_branch .LBB0_1003

; __device__ __forceinline__ unsigned cvt_pk_bf16(float lo, float hi) { unsigned r; asm volatile("v_cvt_pk_bf16_f32 %0, %1, %2" : "=v"(r) : "v"(lo), "v"(hi)); return r; }
;     __device__ __forceinline__ void operator()(const f32x4 (&acc)[2][2][4][2], const Unit& u, int wr, int wc, int fr, int fq) const {
;     ...
;             for (int ai = 0; ai < 2; ++ai)
; #pragma unroll
;                 for (int m = 0; m < 4; ++m) {
;                     const int row = row0 + ai * HALF + m * 16;
;                     const float* gp = gate + (size_t)modrow_of(row) * NMOD + col0;
;                     bf16_t* op = (bf16_t*)((char*)X + SLAB_MINUS_X) + ((size_t)u.kp * MS + (row - MP)) * DM + col0;
; #pragma unroll
;                     for (int bj = 0; bj < 2; ++bj) {
;                         const f32x4 g0 = (*(const f32x4*)(gp + bj * HALF) + *(const f32x4*)(gp + MODSB_DELTA + bj * HALF)) * coef, g1 = (*(const f32x4*)(gp + bj * HALF + 4) + *(const f32x4*)(gp + MODSB_DELTA + bj * HALF + 4)) * coef;
;                         const f32x4 o0 = g0 * acc[ai][bj][m][0], o1 = g1 * acc[ai][bj][m][1];
;                         u32x4 w; w.x = cvt_pk_bf16(o0[0], o0[1]); w.y = cvt_pk_bf16(o0[2], o0[3]); w.z = cvt_pk_bf16(o1[0], o1[1]); w.w = cvt_pk_bf16(o1[2], o1[3]);
;                         *(u32x4*)(op + bj * HALF) = w;
;                     }
.LBB0_1190:
	s_lshl_b32 s19, s28, 8
	s_nop 15
	s_nop 15
	s_add_i32 s19, s19, s68
	v_or_b32_e32 v10, s19, v183
	v_lshl_or_b32 v8, s52, 8, v186
	s_mov_b64 s[34:35], -1
	s_andn2_b64 vcc, exec, s[54:55]
	v_ashrrev_i32_e32 v9, 31, v8
	v_or_b32_e32 v6, 16, v10
	v_or_b32_e32 v4, 32, v10
	v_or_b32_e32 v2, 48, v10
	s_cbranch_vccnz .LBB0_1193
	v_add_u32_e32 v174, 0xffffe000, v10
	s_ashr_i32 s21, s19, 11
	v_lshrrev_b32_e32 v3, 2, v174
	v_or_b32_e32 v5, 4, v3
	v_mov_b32_e32 v3, s21
	v_cmp_gt_i32_e32 vcc, s64, v10
	v_mov_b64_e32 v[14:15], s[8:9]
	v_lshlrev_b64 v[16:17], 2, v[8:9]
	v_cndmask_b32_e32 v5, v5, v3, vcc
	v_mad_i64_i32 v[12:13], s[34:35], v5, s65, v[14:15]
	v_lshl_add_u64 v[176:177], v[12:13], 0, v[16:17]
	v_add_co_u32_e32 v178, vcc, s73, v176
	v_lshl_add_u64 v[12:13], v[176:177], 0, s[14:15]
	s_nop 0
	v_addc_co_u32_e32 v179, vcc, 0, v177, vcc
	global_load_dwordx4 v[18:21], v[176:177], off offset:16
	global_load_dwordx4 v[22:25], v[176:177], off
	global_load_dwordx4 v[26:29], v[178:179], off
	global_load_dwordx4 v[30:33], v[12:13], off offset:16
	global_load_dwordx4 v[230:233], v[176:177], off offset:528
	global_load_dwordx4 v[234:237], v[176:177], off offset:512
	global_load_dwordx4 v[238:241], v[178:179], off offset:512
	v_lshl_add_u64 v[246:247], v[176:177], 0, s[16:17]
	s_nop 0
	global_load_dwordx4 v[242:245], v[246:247], off offset:16
	s_mov_b32 s31, s1
	s_lshl_b64 s[30:31], s[30:31], 21
	v_ashrrev_i32_e32 v175, 31, v174
	s_add_u32 s30, s66, s30
	v_lshlrev_b64 v[174:175], 12, v[174:175]
	s_addc_u32 s31, s67, s31
	v_lshlrev_b64 v[12:13], 1, v[8:9]
	v_lshl_add_u64 v[174:175], s[30:31], 0, v[174:175]
	v_lshl_add_u64 v[174:175], v[174:175], 0, v[12:13]
	v_cmp_gt_i32_e32 vcc, s64, v6
	s_addk_i32 s19, 0x80
	s_movk_i32 s21, 0x1f80
	s_ashr_i32 s19, s19, 11
	s_waitcnt vmcnt(4)
	v_pk_add_f32 v[24:25], v[24:25], v[28:29]
	v_pk_add_f32 v[20:21], v[20:21], v[32:33]
	v_pk_add_f32 v[18:19], v[18:19], v[30:31]
	v_pk_add_f32 v[22:23], v[22:23], v[26:27]
	v_pk_mul_f32 v[26:27], v[156:157], v[20:21]
	v_pk_mul_f32 v[20:21], v[154:155], v[18:19]
	v_pk_mul_f32 v[24:25], v[160:161], v[24:25]
	v_pk_mul_f32 v[22:23], v[158:159], v[22:23]
	v_lshl_add_u64 v[30:31], v[176:177], 0, s[16:17]
	v_cvt_pk_bf16_f32 v18, v22, v23
	v_cvt_pk_bf16_f32 v19, v24, v25
	v_cvt_pk_bf16_f32 v20, v20, v21
	v_cvt_pk_bf16_f32 v21, v26, v27
	global_store_dwordx4 v[174:175], v[18:21], off
	v_add_u32_e32 v176, 0xffffe010, v10
	v_lshrrev_b32_e32 v5, 2, v176
	v_add_u32_e32 v5, 4, v5
	v_cndmask_b32_e32 v5, v5, v3, vcc
	v_mad_i64_i32 v[178:179], s[34:35], v5, s65, v[14:15]
	v_lshl_add_u64 v[178:179], v[178:179], 0, v[16:17]
	v_add_co_u32_e32 v180, vcc, s73, v178
	v_ashrrev_i32_e32 v177, 31, v176
	s_nop 0
	v_addc_co_u32_e32 v181, vcc, 0, v179, vcc
	v_cmp_gt_i32_e32 vcc, s64, v4
	s_nop 1
	s_waitcnt vmcnt(1)
	v_pk_add_f32 v[24:25], v[236:237], v[240:241]
	v_pk_add_f32 v[22:23], v[234:235], v[238:239]
	v_pk_add_f32 v[20:21], v[232:233], v[244:245]
	v_pk_add_f32 v[18:19], v[230:231], v[242:243]
	v_pk_mul_f32 v[26:27], v[144:145], v[20:21]
	v_pk_mul_f32 v[20:21], v[142:143], v[18:19]
	v_pk_mul_f32 v[24:25], v[148:149], v[24:25]
	v_pk_mul_f32 v[22:23], v[146:147], v[22:23]
	v_lshl_add_u64 v[30:31], v[178:179], 0, s[14:15]
	v_cvt_pk_bf16_f32 v18, v22, v23
	v_cvt_pk_bf16_f32 v19, v24, v25
	v_cvt_pk_bf16_f32 v20, v20, v21
	v_cvt_pk_bf16_f32 v21, v26, v27
	global_store_dwordx4 v[174:175], v[18:21], off offset:256
	global_load_dwordx4 v[18:21], v[178:179], off offset:16
	s_nop 0
	global_load_dwordx4 v[22:25], v[178:179], off
	global_load_dwordx4 v[26:29], v[180:181], off
	v_lshlrev_b64 v[174:175], 12, v[176:177]
	global_load_dwordx4 v[30:33], v[30:31], off offset:16
	global_load_dwordx4 v[230:233], v[178:179], off offset:528
	global_load_dwordx4 v[234:237], v[178:179], off offset:512
	global_load_dwordx4 v[238:241], v[180:181], off offset:512
	v_lshl_add_u64 v[246:247], v[178:179], 0, s[16:17]
	s_nop 0
	global_load_dwordx4 v[242:245], v[246:247], off offset:16
	v_lshl_add_u64 v[174:175], s[30:31], 0, v[174:175]
	v_lshl_add_u64 v[174:175], v[174:175], 0, v[12:13]
	v_add_u32_e32 v176, 0xffffe020, v10
	v_lshrrev_b32_e32 v5, 2, v176
	v_or_b32_e32 v5, 4, v5
	v_cndmask_b32_e32 v5, v5, v3, vcc
	v_ashrrev_i32_e32 v177, 31, v176
	s_waitcnt vmcnt(4)
	v_pk_add_f32 v[24:25], v[24:25], v[28:29]
	v_pk_add_f32 v[22:23], v[22:23], v[26:27]
	v_pk_add_f32 v[20:21], v[20:21], v[32:33]
	v_pk_add_f32 v[18:19], v[18:19], v[30:31]
	v_pk_mul_f32 v[26:27], v[140:141], v[20:21]
	v_pk_mul_f32 v[20:21], v[138:139], v[18:19]
	v_pk_mul_f32 v[24:25], v[152:153], v[24:25]
	v_pk_mul_f32 v[22:23], v[150:151], v[22:23]
	v_lshl_add_u64 v[30:31], v[178:179], 0, s[16:17]
	v_cvt_pk_bf16_f32 v18, v22, v23
	v_cvt_pk_bf16_f32 v19, v24, v25
	v_cvt_pk_bf16_f32 v20, v20, v21
	v_cvt_pk_bf16_f32 v21, v26, v27
	global_store_dwordx4 v[174:175], v[18:21], off
	v_mad_i64_i32 v[178:179], s[34:35], v5, s65, v[14:15]
	v_lshl_add_u64 v[178:179], v[178:179], 0, v[16:17]
	v_add_co_u32_e32 v180, vcc, s73, v178
	s_nop 1
	s_waitcnt vmcnt(1)
; __device__ __forceinline__ unsigned cvt_pk_bf16(float lo, float hi) { unsigned r; asm volatile("v_cvt_pk_bf16_f32 %0, %1, %2" : "=v"(r) : "v"(lo), "v"(hi)); return r; }
;     __device__ __forceinline__ void operator()(const f32x4 (&acc)[2][2][4][2], const Unit& u, int wr, int wc, int fr, int fq) const {
;     ...
;             for (int ai = 0; ai < 2; ++ai)
; #pragma unroll
;                 for (int m = 0; m < 4; ++m) {
;                     const int row = row0 + ai * HALF + m * 16;
;                     const float* gp = gate + (size_t)modrow_of(row) * NMOD + col0;
;                     bf16_t* op = (bf16_t*)((char*)X + SLAB_MINUS_X) + ((size_t)u.kp * MS + (row - MP)) * DM + col0;
; #pragma unroll
;                     for (int bj = 0; bj < 2; ++bj) {
;                         const f32x4 g0 = (*(const f32x4*)(gp + bj * HALF) + *(const f32x4*)(gp + MODSB_DELTA + bj * HALF)) * coef, g1 = (*(const f32x4*)(gp + bj * HALF + 4) + *(const f32x4*)(gp + MODSB_DELTA + bj * HALF + 4)) * coef;
;                         const f32x4 o0 = g0 * acc[ai][bj][m][0], o1 = g1 * acc[ai][bj][m][1];
;                         u32x4 w; w.x = cvt_pk_bf16(o0[0], o0[1]); w.y = cvt_pk_bf16(o0[2], o0[3]); w.z = cvt_pk_bf16(o1[0], o1[1]); w.w = cvt_pk_bf16(o1[2], o1[3]);
;                         *(u32x4*)(op + bj * HALF) = w;
;                     }
	v_pk_add_f32 v[24:25], v[236:237], v[240:241]
	v_pk_add_f32 v[22:23], v[234:235], v[238:239]
	v_pk_mul_f32 v[24:25], v[136:137], v[24:25]
	v_pk_add_f32 v[20:21], v[232:233], v[244:245]
	v_pk_add_f32 v[18:19], v[230:231], v[242:243]
	v_pk_mul_f32 v[26:27], v[128:129], v[20:21]
	v_pk_mul_f32 v[20:21], v[126:127], v[18:19]
	v_pk_mul_f32 v[22:23], v[134:135], v[22:23]
	v_lshl_add_u64 v[30:31], v[178:179], 0, s[14:15]
	v_cvt_pk_bf16_f32 v18, v22, v23
	v_cvt_pk_bf16_f32 v19, v24, v25
	v_cvt_pk_bf16_f32 v20, v20, v21
	v_cvt_pk_bf16_f32 v21, v26, v27
	global_store_dwordx4 v[174:175], v[18:21], off offset:256
	v_addc_co_u32_e32 v181, vcc, 0, v179, vcc
	global_load_dwordx4 v[18:21], v[178:179], off offset:16
	global_load_dwordx4 v[22:25], v[178:179], off
	global_load_dwordx4 v[26:29], v[180:181], off
	v_lshlrev_b64 v[174:175], 12, v[176:177]
	global_load_dwordx4 v[30:33], v[30:31], off offset:16
	global_load_dwordx4 v[230:233], v[178:179], off offset:528
	global_load_dwordx4 v[234:237], v[178:179], off offset:512
	global_load_dwordx4 v[238:241], v[180:181], off offset:512
	v_lshl_add_u64 v[246:247], v[178:179], 0, s[16:17]
	s_nop 0
	global_load_dwordx4 v[242:245], v[246:247], off offset:16
	v_lshl_add_u64 v[174:175], s[30:31], 0, v[174:175]
	v_lshl_add_u64 v[174:175], v[174:175], 0, v[12:13]
	v_add_u32_e32 v176, 0xffffe030, v10
	v_lshrrev_b32_e32 v5, 2, v176
	v_add_u32_e32 v5, 4, v5
	v_cmp_gt_i32_e32 vcc, s64, v2
	v_ashrrev_i32_e32 v177, 31, v176
	s_waitcnt vmcnt(4)
	v_pk_add_f32 v[24:25], v[24:25], v[28:29]
	v_pk_add_f32 v[22:23], v[22:23], v[26:27]
	v_pk_add_f32 v[20:21], v[20:21], v[32:33]
	v_pk_add_f32 v[18:19], v[18:19], v[30:31]
	v_pk_mul_f32 v[26:27], v[124:125], v[20:21]
	v_pk_mul_f32 v[20:21], v[122:123], v[18:19]
	v_pk_mul_f32 v[24:25], v[132:133], v[24:25]
	v_pk_mul_f32 v[22:23], v[130:131], v[22:23]
	v_lshl_add_u64 v[30:31], v[178:179], 0, s[16:17]
	v_cvt_pk_bf16_f32 v18, v22, v23
	v_cvt_pk_bf16_f32 v19, v24, v25
	v_cvt_pk_bf16_f32 v20, v20, v21
	v_cvt_pk_bf16_f32 v21, v26, v27
	global_store_dwordx4 v[174:175], v[18:21], off
	v_cndmask_b32_e32 v3, v5, v3, vcc
	v_mad_i64_i32 v[178:179], s[34:35], v3, s65, v[14:15]
	v_lshl_add_u64 v[178:179], v[178:179], 0, v[16:17]
	v_add_co_u32_e32 v180, vcc, s73, v178
	s_nop 1
	s_waitcnt vmcnt(1)
	v_pk_add_f32 v[24:25], v[236:237], v[240:241]
	v_pk_add_f32 v[22:23], v[234:235], v[238:239]
	v_pk_add_f32 v[20:21], v[232:233], v[244:245]
	v_pk_add_f32 v[18:19], v[230:231], v[242:243]
	v_pk_mul_f32 v[26:27], v[112:113], v[20:21]
	v_pk_mul_f32 v[20:21], v[110:111], v[18:19]
	v_pk_mul_f32 v[24:25], v[116:117], v[24:25]
	v_pk_mul_f32 v[22:23], v[114:115], v[22:23]
	v_lshl_add_u64 v[30:31], v[178:179], 0, s[14:15]
	v_cvt_pk_bf16_f32 v18, v22, v23
	v_cvt_pk_bf16_f32 v19, v24, v25
	v_cvt_pk_bf16_f32 v20, v20, v21
	v_cvt_pk_bf16_f32 v21, v26, v27
	global_store_dwordx4 v[174:175], v[18:21], off offset:256
	v_addc_co_u32_e32 v181, vcc, 0, v179, vcc
	global_load_dwordx4 v[18:21], v[178:179], off offset:16
	global_load_dwordx4 v[22:25], v[178:179], off
	global_load_dwordx4 v[26:29], v[180:181], off
	v_lshlrev_b64 v[174:175], 12, v[176:177]
	global_load_dwordx4 v[30:33], v[30:31], off offset:16
	global_load_dwordx4 v[230:233], v[178:179], off offset:528
	global_load_dwordx4 v[234:237], v[178:179], off offset:512
	global_load_dwordx4 v[238:241], v[180:181], off offset:512
	v_lshl_add_u64 v[246:247], v[178:179], 0, s[16:17]
	s_nop 0
	global_load_dwordx4 v[242:245], v[246:247], off offset:16
	v_lshl_add_u64 v[174:175], s[30:31], 0, v[174:175]
	v_lshl_add_u64 v[174:175], v[174:175], 0, v[12:13]
	v_add_u32_e32 v176, 0xffffe080, v10
	v_lshrrev_b32_e32 v3, 2, v176
	v_or_b32_e32 v5, 4, v3
	v_mov_b32_e32 v3, s19
	v_cmp_gt_i32_e32 vcc, s21, v10
	v_ashrrev_i32_e32 v177, 31, v176
	s_movk_i32 s19, 0x1f70
	v_cndmask_b32_e32 v5, v5, v3, vcc
	s_waitcnt vmcnt(4)
	v_pk_add_f32 v[24:25], v[24:25], v[28:29]
	v_pk_add_f32 v[22:23], v[22:23], v[26:27]
	v_pk_add_f32 v[20:21], v[20:21], v[32:33]
	v_pk_add_f32 v[18:19], v[18:19], v[30:31]
	v_pk_mul_f32 v[26:27], v[108:109], v[20:21]
	v_pk_mul_f32 v[20:21], v[106:107], v[18:19]
	v_pk_mul_f32 v[24:25], v[120:121], v[24:25]
	v_pk_mul_f32 v[22:23], v[118:119], v[22:23]
	v_lshl_add_u64 v[30:31], v[178:179], 0, s[16:17]
	v_cvt_pk_bf16_f32 v18, v22, v23
	v_cvt_pk_bf16_f32 v19, v24, v25
	v_cvt_pk_bf16_f32 v20, v20, v21
	v_cvt_pk_bf16_f32 v21, v26, v27
	global_store_dwordx4 v[174:175], v[18:21], off
	v_mad_i64_i32 v[178:179], s[34:35], v5, s65, v[14:15]
	v_lshl_add_u64 v[178:179], v[178:179], 0, v[16:17]
	v_add_co_u32_e32 v180, vcc, s73, v178
	s_nop 1
	s_waitcnt vmcnt(1)
	v_pk_add_f32 v[24:25], v[236:237], v[240:241]
	v_pk_add_f32 v[22:23], v[234:235], v[238:239]
	v_pk_mul_f32 v[24:25], v[104:105], v[24:25]
	v_pk_add_f32 v[20:21], v[232:233], v[244:245]
	v_pk_add_f32 v[18:19], v[230:231], v[242:243]
	v_pk_mul_f32 v[26:27], v[100:101], v[20:21]
	v_pk_mul_f32 v[20:21], v[98:99], v[18:19]
	v_pk_mul_f32 v[22:23], v[102:103], v[22:23]
	v_lshl_add_u64 v[30:31], v[178:179], 0, s[14:15]
	v_cvt_pk_bf16_f32 v18, v22, v23
	v_cvt_pk_bf16_f32 v19, v24, v25
	v_cvt_pk_bf16_f32 v20, v20, v21
	v_cvt_pk_bf16_f32 v21, v26, v27
	global_store_dwordx4 v[174:175], v[18:21], off offset:256
	v_addc_co_u32_e32 v181, vcc, 0, v179, vcc
	global_load_dwordx4 v[18:21], v[178:179], off offset:16
	global_load_dwordx4 v[22:25], v[178:179], off
	global_load_dwordx4 v[26:29], v[180:181], off
	v_lshlrev_b64 v[174:175], 12, v[176:177]
	global_load_dwordx4 v[30:33], v[30:31], off offset:16
	global_load_dwordx4 v[230:233], v[178:179], off offset:528
	global_load_dwordx4 v[234:237], v[178:179], off offset:512
	global_load_dwordx4 v[238:241], v[180:181], off offset:512
	v_lshl_add_u64 v[246:247], v[178:179], 0, s[16:17]
	s_nop 0
	global_load_dwordx4 v[242:245], v[246:247], off offset:16
	v_lshl_add_u64 v[174:175], s[30:31], 0, v[174:175]
	v_lshl_add_u64 v[174:175], v[174:175], 0, v[12:13]
	v_add_u32_e32 v176, 0xffffe090, v10
	v_lshrrev_b32_e32 v5, 2, v176
	v_add_u32_e32 v5, 4, v5
	v_cmp_gt_i32_e32 vcc, s19, v10
	v_ashrrev_i32_e32 v177, 31, v176
	s_movk_i32 s19, 0x1f60
	v_cndmask_b32_e32 v5, v5, v3, vcc
	s_waitcnt vmcnt(4)
; __device__ __forceinline__ unsigned cvt_pk_bf16(float lo, float hi) { unsigned r; asm volatile("v_cvt_pk_bf16_f32 %0, %1, %2" : "=v"(r) : "v"(lo), "v"(hi)); return r; }
;     __device__ __forceinline__ void operator()(const f32x4 (&acc)[2][2][4][2], const Unit& u, int wr, int wc, int fr, int fq) const {
;     ...
;                 for (int m = 0; m < 4; ++m) {
;                     const int row = row0 + ai * HALF + m * 16;
;                     const float* gp = gate + (size_t)modrow_of(row) * NMOD + col0;
;                     bf16_t* op = (bf16_t*)((char*)X + SLAB_MINUS_X) + ((size_t)u.kp * MS + (row - MP)) * DM + col0;
; #pragma unroll
;                     for (int bj = 0; bj < 2; ++bj) {
;                         const f32x4 g0 = (*(const f32x4*)(gp + bj * HALF) + *(const f32x4*)(gp + MODSB_DELTA + bj * HALF)) * coef, g1 = (*(const f32x4*)(gp + bj * HALF + 4) + *(const f32x4*)(gp + MODSB_DELTA + bj * HALF + 4)) * coef;
;                         const f32x4 o0 = g0 * acc[ai][bj][m][0], o1 = g1 * acc[ai][bj][m][1];
;                         u32x4 w; w.x = cvt_pk_bf16(o0[0], o0[1]); w.y = cvt_pk_bf16(o0[2], o0[3]); w.z = cvt_pk_bf16(o1[0], o1[1]); w.w = cvt_pk_bf16(o1[2], o1[3]);
;                         *(u32x4*)(op + bj * HALF) = w;
;                     }
;                     if (m & 1) asm volatile("" ::: "memory");
	v_pk_add_f32 v[24:25], v[24:25], v[28:29]
	v_pk_add_f32 v[22:23], v[22:23], v[26:27]
	v_pk_add_f32 v[20:21], v[20:21], v[32:33]
	v_pk_add_f32 v[18:19], v[18:19], v[30:31]
	v_pk_mul_f32 v[26:27], v[92:93], v[20:21]
	v_pk_mul_f32 v[20:21], v[90:91], v[18:19]
	v_pk_mul_f32 v[24:25], v[96:97], v[24:25]
	v_pk_mul_f32 v[22:23], v[94:95], v[22:23]
	v_lshl_add_u64 v[30:31], v[178:179], 0, s[16:17]
	v_cvt_pk_bf16_f32 v18, v22, v23
	v_cvt_pk_bf16_f32 v19, v24, v25
	v_cvt_pk_bf16_f32 v20, v20, v21
	v_cvt_pk_bf16_f32 v21, v26, v27
	global_store_dwordx4 v[174:175], v[18:21], off
	v_mad_i64_i32 v[178:179], s[34:35], v5, s65, v[14:15]
	v_lshl_add_u64 v[178:179], v[178:179], 0, v[16:17]
	v_add_co_u32_e32 v180, vcc, s73, v178
	s_nop 1
	s_waitcnt vmcnt(1)
	v_pk_add_f32 v[24:25], v[236:237], v[240:241]
	v_pk_add_f32 v[22:23], v[234:235], v[238:239]
	v_pk_mul_f32 v[24:25], v[88:89], v[24:25]
	v_pk_add_f32 v[20:21], v[232:233], v[244:245]
	v_pk_add_f32 v[18:19], v[230:231], v[242:243]
	v_pk_mul_f32 v[26:27], v[80:81], v[20:21]
	v_pk_mul_f32 v[20:21], v[78:79], v[18:19]
	v_pk_mul_f32 v[22:23], v[86:87], v[22:23]
	v_lshl_add_u64 v[30:31], v[178:179], 0, s[14:15]
	v_cvt_pk_bf16_f32 v18, v22, v23
	v_cvt_pk_bf16_f32 v19, v24, v25
	v_cvt_pk_bf16_f32 v20, v20, v21
	v_cvt_pk_bf16_f32 v21, v26, v27
	global_store_dwordx4 v[174:175], v[18:21], off offset:256
	v_addc_co_u32_e32 v181, vcc, 0, v179, vcc
	global_load_dwordx4 v[18:21], v[178:179], off offset:16
	global_load_dwordx4 v[22:25], v[178:179], off
	global_load_dwordx4 v[26:29], v[180:181], off
	v_lshlrev_b64 v[174:175], 12, v[176:177]
	global_load_dwordx4 v[30:33], v[30:31], off offset:16
	global_load_dwordx4 v[230:233], v[178:179], off offset:528
	global_load_dwordx4 v[234:237], v[178:179], off offset:512
	global_load_dwordx4 v[238:241], v[180:181], off offset:512
	v_lshl_add_u64 v[246:247], v[178:179], 0, s[16:17]
	s_nop 0
	global_load_dwordx4 v[242:245], v[246:247], off offset:16
	v_lshl_add_u64 v[174:175], s[30:31], 0, v[174:175]
	v_lshl_add_u64 v[174:175], v[174:175], 0, v[12:13]
	v_add_u32_e32 v176, 0xffffe0a0, v10
	v_lshrrev_b32_e32 v5, 2, v176
	v_or_b32_e32 v5, 4, v5
	v_cmp_gt_i32_e32 vcc, s19, v10
	v_ashrrev_i32_e32 v177, 31, v176
	s_movk_i32 s19, 0x1f50
	v_cndmask_b32_e32 v5, v5, v3, vcc
	s_waitcnt vmcnt(4)
	v_pk_add_f32 v[24:25], v[24:25], v[28:29]
	v_pk_add_f32 v[22:23], v[22:23], v[26:27]
	v_pk_add_f32 v[20:21], v[20:21], v[32:33]
	v_pk_add_f32 v[18:19], v[18:19], v[30:31]
	v_pk_mul_f32 v[26:27], v[76:77], v[20:21]
	v_pk_mul_f32 v[20:21], v[74:75], v[18:19]
	v_pk_mul_f32 v[24:25], v[84:85], v[24:25]
	v_pk_mul_f32 v[22:23], v[82:83], v[22:23]
	v_lshl_add_u64 v[30:31], v[178:179], 0, s[16:17]
	v_cvt_pk_bf16_f32 v18, v22, v23
	v_cvt_pk_bf16_f32 v19, v24, v25
	v_cvt_pk_bf16_f32 v20, v20, v21
	v_cvt_pk_bf16_f32 v21, v26, v27
	global_store_dwordx4 v[174:175], v[18:21], off
	v_mad_i64_i32 v[178:179], s[34:35], v5, s65, v[14:15]
	v_lshl_add_u64 v[178:179], v[178:179], 0, v[16:17]
	v_add_co_u32_e32 v180, vcc, s73, v178
	s_nop 1
	s_waitcnt vmcnt(1)
	v_pk_add_f32 v[24:25], v[236:237], v[240:241]
	v_pk_add_f32 v[22:23], v[234:235], v[238:239]
	v_pk_mul_f32 v[24:25], v[72:73], v[24:25]
	v_pk_add_f32 v[20:21], v[232:233], v[244:245]
	v_pk_add_f32 v[18:19], v[230:231], v[242:243]
	v_pk_mul_f32 v[26:27], v[64:65], v[20:21]
	v_pk_mul_f32 v[20:21], v[62:63], v[18:19]
	v_pk_mul_f32 v[22:23], v[70:71], v[22:23]
	v_lshl_add_u64 v[30:31], v[178:179], 0, s[14:15]
	v_cvt_pk_bf16_f32 v18, v22, v23
	v_cvt_pk_bf16_f32 v19, v24, v25
	v_cvt_pk_bf16_f32 v20, v20, v21
	v_cvt_pk_bf16_f32 v21, v26, v27
	global_store_dwordx4 v[174:175], v[18:21], off offset:256
	v_addc_co_u32_e32 v181, vcc, 0, v179, vcc
	global_load_dwordx4 v[18:21], v[178:179], off offset:16
	global_load_dwordx4 v[22:25], v[178:179], off
	global_load_dwordx4 v[26:29], v[180:181], off
	v_lshlrev_b64 v[174:175], 12, v[176:177]
	global_load_dwordx4 v[30:33], v[30:31], off offset:16
	global_load_dwordx4 v[230:233], v[178:179], off offset:528
	global_load_dwordx4 v[234:237], v[178:179], off offset:512
	global_load_dwordx4 v[238:241], v[180:181], off offset:512
	v_lshl_add_u64 v[246:247], v[178:179], 0, s[16:17]
	s_nop 0
	global_load_dwordx4 v[242:245], v[246:247], off offset:16
	v_lshl_add_u64 v[174:175], s[30:31], 0, v[174:175]
	v_lshl_add_u64 v[174:175], v[174:175], 0, v[12:13]
	v_add_u32_e32 v176, 0xffffe0b0, v10
	v_lshrrev_b32_e32 v5, 2, v176
	v_add_u32_e32 v5, 4, v5
	v_cmp_gt_i32_e32 vcc, s19, v10
	v_ashrrev_i32_e32 v177, 31, v176
	s_waitcnt vmcnt(4)
; __device__ __forceinline__ unsigned cvt_pk_bf16(float lo, float hi) { unsigned r; asm volatile("v_cvt_pk_bf16_f32 %0, %1, %2" : "=v"(r) : "v"(lo), "v"(hi)); return r; }
;     __device__ __forceinline__ void operator()(const f32x4 (&acc)[2][2][4][2], const Unit& u, int wr, int wc, int fr, int fq) const {
;     ...
;                 for (int m = 0; m < 4; ++m) {
;                     const int row = row0 + ai * HALF + m * 16;
;                     const float* gp = gate + (size_t)modrow_of(row) * NMOD + col0;
;                     bf16_t* op = (bf16_t*)((char*)X + SLAB_MINUS_X) + ((size_t)u.kp * MS + (row - MP)) * DM + col0;
; #pragma unroll
;                     for (int bj = 0; bj < 2; ++bj) {
;                         const f32x4 g0 = (*(const f32x4*)(gp + bj * HALF) + *(const f32x4*)(gp + MODSB_DELTA + bj * HALF)) * coef, g1 = (*(const f32x4*)(gp + bj * HALF + 4) + *(const f32x4*)(gp + MODSB_DELTA + bj * HALF + 4)) * coef;
;                         const f32x4 o0 = g0 * acc[ai][bj][m][0], o1 = g1 * acc[ai][bj][m][1];
;                         u32x4 w; w.x = cvt_pk_bf16(o0[0], o0[1]); w.y = cvt_pk_bf16(o0[2], o0[3]); w.z = cvt_pk_bf16(o1[0], o1[1]); w.w = cvt_pk_bf16(o1[2], o1[3]);
;                         *(u32x4*)(op + bj * HALF) = w;
;                     }
;                     if (m & 1) asm volatile("" ::: "memory");
;                 }
	v_pk_add_f32 v[24:25], v[24:25], v[28:29]
	v_pk_add_f32 v[22:23], v[22:23], v[26:27]
	v_pk_add_f32 v[20:21], v[20:21], v[32:33]
	v_pk_add_f32 v[18:19], v[18:19], v[30:31]
	v_pk_mul_f32 v[26:27], v[60:61], v[20:21]
	v_pk_mul_f32 v[20:21], v[58:59], v[18:19]
	v_pk_mul_f32 v[24:25], v[68:69], v[24:25]
	v_pk_mul_f32 v[22:23], v[66:67], v[22:23]
	v_lshl_add_u64 v[30:31], v[178:179], 0, s[16:17]
	v_cvt_pk_bf16_f32 v18, v22, v23
	v_cvt_pk_bf16_f32 v19, v24, v25
	v_cvt_pk_bf16_f32 v20, v20, v21
	v_cvt_pk_bf16_f32 v21, v26, v27
	global_store_dwordx4 v[174:175], v[18:21], off
	v_cndmask_b32_e32 v3, v5, v3, vcc
	v_mad_i64_i32 v[14:15], s[34:35], v3, s65, v[14:15]
	v_lshl_add_u64 v[178:179], v[14:15], 0, v[16:17]
	v_add_co_u32_e32 v180, vcc, s73, v178
	s_nop 1
	v_addc_co_u32_e32 v181, vcc, 0, v179, vcc
	s_nop 1
	s_waitcnt vmcnt(1)
	v_pk_add_f32 v[14:15], v[236:237], v[240:241]
	v_pk_add_f32 v[16:17], v[234:235], v[238:239]
	v_pk_add_f32 v[18:19], v[230:231], v[242:243]
	v_pk_add_f32 v[20:21], v[232:233], v[244:245]
	v_pk_mul_f32 v[22:23], v[56:57], v[14:15]
	v_pk_mul_f32 v[14:15], v[54:55], v[16:17]
	v_pk_mul_f32 v[16:17], v[46:47], v[18:19]
	v_pk_mul_f32 v[20:21], v[48:49], v[20:21]
	v_cvt_pk_bf16_f32 v14, v14, v15
	v_cvt_pk_bf16_f32 v15, v22, v23
	v_cvt_pk_bf16_f32 v16, v16, v17
	v_lshl_add_u64 v[26:27], v[178:179], 0, s[14:15]
	v_cvt_pk_bf16_f32 v17, v20, v21
	global_store_dwordx4 v[174:175], v[14:17], off offset:256
	global_load_dwordx4 v[14:17], v[178:179], off offset:16
	s_nop 0
	global_load_dwordx4 v[18:21], v[178:179], off
	global_load_dwordx4 v[22:25], v[180:181], off
	v_lshlrev_b64 v[30:31], 12, v[176:177]
	global_load_dwordx4 v[26:29], v[26:27], off offset:16
	global_load_dwordx4 v[230:233], v[178:179], off offset:528
	global_load_dwordx4 v[234:237], v[178:179], off offset:512
	global_load_dwordx4 v[238:241], v[180:181], off offset:512
	v_lshl_add_u64 v[246:247], v[178:179], 0, s[16:17]
	s_nop 0
	global_load_dwordx4 v[242:245], v[246:247], off offset:16
	v_lshl_add_u64 v[30:31], s[30:31], 0, v[30:31]
	v_lshl_add_u64 v[30:31], v[30:31], 0, v[12:13]
	s_waitcnt vmcnt(4)
	v_pk_add_f32 v[12:13], v[20:21], v[24:25]
	v_pk_add_f32 v[18:19], v[18:19], v[22:23]
	v_pk_add_f32 v[14:15], v[14:15], v[26:27]
	v_pk_add_f32 v[16:17], v[16:17], v[28:29]
	v_pk_mul_f32 v[20:21], v[52:53], v[12:13]
	v_pk_mul_f32 v[12:13], v[50:51], v[18:19]
	v_pk_mul_f32 v[14:15], v[42:43], v[14:15]
	v_pk_mul_f32 v[16:17], v[44:45], v[16:17]
	v_cvt_pk_bf16_f32 v12, v12, v13
	v_cvt_pk_bf16_f32 v13, v20, v21
	v_cvt_pk_bf16_f32 v14, v14, v15
	v_lshl_add_u64 v[24:25], v[178:179], 0, s[16:17]
	v_cvt_pk_bf16_f32 v15, v16, v17
	global_store_dwordx4 v[30:31], v[12:15], off
	s_waitcnt vmcnt(1)
	v_pk_add_f32 v[18:19], v[236:237], v[240:241]
	v_pk_add_f32 v[16:17], v[234:235], v[238:239]
	v_pk_mul_f32 v[18:19], v[40:41], v[18:19]
	v_pk_mul_f32 v[16:17], v[38:39], v[16:17]
	s_nop 1
	s_waitcnt vmcnt(1)
	v_pk_add_f32 v[14:15], v[232:233], v[244:245]
	v_pk_add_f32 v[12:13], v[230:231], v[242:243]
	v_pk_mul_f32 v[20:21], v[36:37], v[14:15]
	v_pk_mul_f32 v[14:15], v[34:35], v[12:13]
	v_cvt_pk_bf16_f32 v12, v16, v17
	v_cvt_pk_bf16_f32 v13, v18, v19
	s_nop 0
	v_cvt_pk_bf16_f32 v14, v14, v15
	v_cvt_pk_bf16_f32 v15, v20, v21
	global_store_dwordx4 v[30:31], v[12:15], off offset:256
	s_cbranch_execz .LBB0_1194

; __device__ __forceinline__ unsigned cvt_pk_bf16(float lo, float hi) { unsigned r; asm volatile("v_cvt_pk_bf16_f32 %0, %1, %2" : "=v"(r) : "v"(lo), "v"(hi)); return r; }
;     __device__ __forceinline__ void operator()(const f32x4 (&acc)[2][2][4][2], const Unit& u, int wr, int wc, int fr, int fq) const {
;         const int row0 = u.pm * BM + wr * 64 + fr, col0 = u.pn * BM + wc * 32 + 8 * fq;
;         if (u.kp < 0) {
;     ...
;                     const int row = row0 + ai * HALF + m * 16;
;                     const float* gp = gate + (size_t)modrow_of(row) * NMOD + col0;
;                     bf16_t* op = (bf16_t*)((char*)X + SLAB_MINUS_X) + ((size_t)u.kp * MS + (row - MP)) * DM + col0;
; #pragma unroll
;                     for (int bj = 0; bj < 2; ++bj) {
;                         const f32x4 g0 = (*(const f32x4*)(gp + bj * HALF) + *(const f32x4*)(gp + MODSB_DELTA + bj * HALF)) * coef, g1 = (*(const f32x4*)(gp + bj * HALF + 4) + *(const f32x4*)(gp + MODSB_DELTA + bj * HALF + 4)) * coef;
;                         const f32x4 o0 = g0 * acc[ai][bj][m][0], o1 = g1 * acc[ai][bj][m][1];
;                         u32x4 w; w.x = cvt_pk_bf16(o0[0], o0[1]); w.y = cvt_pk_bf16(o0[2], o0[3]); w.z = cvt_pk_bf16(o1[0], o1[1]); w.w = cvt_pk_bf16(o1[2], o1[3]);
;                         *(u32x4*)(op + bj * HALF) = w;
;                     }
;                     if (m & 1) asm volatile("" ::: "memory");
.LBB0_1514:
	s_lshl_b32 s38, s77, 8
	s_nop 15
	s_nop 15
	s_add_i32 s38, s38, s60
	v_or_b32_e32 v10, s38, v183
	v_lshl_or_b32 v8, s78, 8, v186
	s_mov_b64 s[34:35], -1
	s_andn2_b64 vcc, exec, s[36:37]
	v_ashrrev_i32_e32 v9, 31, v8
	v_or_b32_e32 v6, 16, v10
	v_or_b32_e32 v4, 32, v10
	v_or_b32_e32 v2, 48, v10
	s_cbranch_vccnz .LBB0_1517
	v_add_u32_e32 v174, 0xffffe000, v10
	s_ashr_i32 s31, s38, 11
	v_lshrrev_b32_e32 v3, 2, v174
	v_or_b32_e32 v3, 4, v3
	v_mov_b32_e32 v5, s31
	v_cmp_gt_i32_e32 vcc, s57, v10
	v_mov_b64_e32 v[14:15], s[10:11]
	v_lshlrev_b64 v[16:17], 2, v[8:9]
	v_cndmask_b32_e32 v3, v3, v5, vcc
	v_mad_i64_i32 v[12:13], s[34:35], v3, s56, v[14:15]
	v_lshl_add_u64 v[176:177], v[12:13], 0, v[16:17]
	v_add_co_u32_e32 v178, vcc, s65, v176
	v_lshl_add_u64 v[12:13], v[176:177], 0, s[16:17]
	s_nop 0
	v_addc_co_u32_e32 v179, vcc, 0, v177, vcc
	global_load_dwordx4 v[18:21], v[176:177], off offset:16
	global_load_dwordx4 v[22:25], v[176:177], off
	global_load_dwordx4 v[26:29], v[178:179], off
	global_load_dwordx4 v[30:33], v[12:13], off offset:16
	global_load_dwordx4 v[230:233], v[176:177], off offset:528
	global_load_dwordx4 v[234:237], v[176:177], off offset:512
	global_load_dwordx4 v[238:241], v[178:179], off offset:512
	v_lshl_add_u64 v[246:247], v[176:177], 0, s[18:19]
	s_nop 0
	global_load_dwordx4 v[242:245], v[246:247], off offset:16
	s_mov_b32 s31, s1
	s_lshl_b64 s[30:31], s[30:31], 21
	v_ashrrev_i32_e32 v175, 31, v174
	s_add_u32 s30, s58, s30
	v_lshlrev_b64 v[174:175], 12, v[174:175]
	s_addc_u32 s31, s59, s31
	v_lshlrev_b64 v[12:13], 1, v[8:9]
	v_lshl_add_u64 v[174:175], s[30:31], 0, v[174:175]
	v_lshl_add_u64 v[174:175], v[174:175], 0, v[12:13]
	v_cmp_gt_i32_e32 vcc, s57, v6
	s_addk_i32 s38, 0x80
	s_waitcnt vmcnt(4)
	v_pk_add_f32 v[24:25], v[24:25], v[28:29]
	v_pk_add_f32 v[20:21], v[20:21], v[32:33]
	v_pk_add_f32 v[18:19], v[18:19], v[30:31]
	v_pk_add_f32 v[22:23], v[22:23], v[26:27]
	v_pk_mul_f32 v[20:21], v[20:21], 0.5 op_sel_hi:[1,0]
	v_pk_mul_f32 v[18:19], v[18:19], 0.5 op_sel_hi:[1,0]
	v_pk_mul_f32 v[24:25], v[24:25], 0.5 op_sel_hi:[1,0]
	v_pk_mul_f32 v[22:23], v[22:23], 0.5 op_sel_hi:[1,0]
	v_pk_mul_f32 v[26:27], v[156:157], v[20:21]
	v_pk_mul_f32 v[20:21], v[154:155], v[18:19]
	v_pk_mul_f32 v[24:25], v[160:161], v[24:25]
	v_pk_mul_f32 v[22:23], v[158:159], v[22:23]
	v_lshl_add_u64 v[30:31], v[176:177], 0, s[18:19]
	v_cvt_pk_bf16_f32 v18, v22, v23
	v_cvt_pk_bf16_f32 v19, v24, v25
	v_cvt_pk_bf16_f32 v20, v20, v21
	v_cvt_pk_bf16_f32 v21, v26, v27
	global_store_dwordx4 v[174:175], v[18:21], off
	v_add_u32_e32 v176, 0xffffe010, v10
	v_lshrrev_b32_e32 v3, 2, v176
	v_add_u32_e32 v3, 4, v3
	v_cndmask_b32_e32 v3, v3, v5, vcc
	v_mad_i64_i32 v[178:179], s[34:35], v3, s56, v[14:15]
	v_lshl_add_u64 v[178:179], v[178:179], 0, v[16:17]
	v_add_co_u32_e32 v180, vcc, s65, v178
	v_ashrrev_i32_e32 v177, 31, v176
	s_nop 0
	v_addc_co_u32_e32 v181, vcc, 0, v179, vcc
	v_cmp_gt_i32_e32 vcc, s57, v4
	s_nop 1
	s_waitcnt vmcnt(1)
	v_pk_add_f32 v[24:25], v[236:237], v[240:241]
	v_pk_add_f32 v[22:23], v[234:235], v[238:239]
	v_pk_add_f32 v[20:21], v[232:233], v[244:245]
	v_pk_add_f32 v[18:19], v[230:231], v[242:243]
	v_pk_mul_f32 v[20:21], v[20:21], 0.5 op_sel_hi:[1,0]
	v_pk_mul_f32 v[18:19], v[18:19], 0.5 op_sel_hi:[1,0]
	v_pk_mul_f32 v[24:25], v[24:25], 0.5 op_sel_hi:[1,0]
	v_pk_mul_f32 v[22:23], v[22:23], 0.5 op_sel_hi:[1,0]
	v_pk_mul_f32 v[26:27], v[144:145], v[20:21]
	v_pk_mul_f32 v[20:21], v[142:143], v[18:19]
	v_pk_mul_f32 v[24:25], v[148:149], v[24:25]
	v_pk_mul_f32 v[22:23], v[146:147], v[22:23]
	v_lshl_add_u64 v[30:31], v[178:179], 0, s[16:17]
	v_cvt_pk_bf16_f32 v18, v22, v23
	v_cvt_pk_bf16_f32 v19, v24, v25
	v_cvt_pk_bf16_f32 v20, v20, v21
	v_cvt_pk_bf16_f32 v21, v26, v27
	global_store_dwordx4 v[174:175], v[18:21], off offset:256
	global_load_dwordx4 v[18:21], v[178:179], off offset:16
	s_nop 0
	global_load_dwordx4 v[22:25], v[178:179], off
	global_load_dwordx4 v[26:29], v[180:181], off
	v_lshlrev_b64 v[174:175], 12, v[176:177]
	global_load_dwordx4 v[30:33], v[30:31], off offset:16
	global_load_dwordx4 v[230:233], v[178:179], off offset:528
	global_load_dwordx4 v[234:237], v[178:179], off offset:512
	global_load_dwordx4 v[238:241], v[180:181], off offset:512
	v_lshl_add_u64 v[246:247], v[178:179], 0, s[18:19]
	s_nop 0
	global_load_dwordx4 v[242:245], v[246:247], off offset:16
	v_lshl_add_u64 v[174:175], s[30:31], 0, v[174:175]
	v_lshl_add_u64 v[174:175], v[174:175], 0, v[12:13]
	v_add_u32_e32 v176, 0xffffe020, v10
	v_lshrrev_b32_e32 v3, 2, v176
	v_or_b32_e32 v3, 4, v3
	v_cndmask_b32_e32 v3, v3, v5, vcc
	v_ashrrev_i32_e32 v177, 31, v176
	s_waitcnt vmcnt(4)
	v_pk_add_f32 v[24:25], v[24:25], v[28:29]
	v_pk_add_f32 v[22:23], v[22:23], v[26:27]
	v_pk_add_f32 v[20:21], v[20:21], v[32:33]
	v_pk_add_f32 v[18:19], v[18:19], v[30:31]
	v_pk_mul_f32 v[20:21], v[20:21], 0.5 op_sel_hi:[1,0]
	v_pk_mul_f32 v[18:19], v[18:19], 0.5 op_sel_hi:[1,0]
	v_pk_mul_f32 v[24:25], v[24:25], 0.5 op_sel_hi:[1,0]
	v_pk_mul_f32 v[22:23], v[22:23], 0.5 op_sel_hi:[1,0]
	v_pk_mul_f32 v[26:27], v[140:141], v[20:21]
	v_pk_mul_f32 v[20:21], v[138:139], v[18:19]
	v_pk_mul_f32 v[24:25], v[152:153], v[24:25]
	v_pk_mul_f32 v[22:23], v[150:151], v[22:23]
	v_lshl_add_u64 v[30:31], v[178:179], 0, s[18:19]
	v_cvt_pk_bf16_f32 v18, v22, v23
	v_cvt_pk_bf16_f32 v19, v24, v25
	v_cvt_pk_bf16_f32 v20, v20, v21
	v_cvt_pk_bf16_f32 v21, v26, v27
	global_store_dwordx4 v[174:175], v[18:21], off
	v_mad_i64_i32 v[178:179], s[34:35], v3, s56, v[14:15]
	v_lshl_add_u64 v[178:179], v[178:179], 0, v[16:17]
	v_add_co_u32_e32 v180, vcc, s65, v178
	s_nop 1
	s_waitcnt vmcnt(1)
; __device__ __forceinline__ unsigned cvt_pk_bf16(float lo, float hi) { unsigned r; asm volatile("v_cvt_pk_bf16_f32 %0, %1, %2" : "=v"(r) : "v"(lo), "v"(hi)); return r; }
;     __device__ __forceinline__ void operator()(const f32x4 (&acc)[2][2][4][2], const Unit& u, int wr, int wc, int fr, int fq) const {
;     ...
;                     const int row = row0 + ai * HALF + m * 16;
;                     const float* gp = gate + (size_t)modrow_of(row) * NMOD + col0;
;                     bf16_t* op = (bf16_t*)((char*)X + SLAB_MINUS_X) + ((size_t)u.kp * MS + (row - MP)) * DM + col0;
; #pragma unroll
;                     for (int bj = 0; bj < 2; ++bj) {
;                         const f32x4 g0 = (*(const f32x4*)(gp + bj * HALF) + *(const f32x4*)(gp + MODSB_DELTA + bj * HALF)) * coef, g1 = (*(const f32x4*)(gp + bj * HALF + 4) + *(const f32x4*)(gp + MODSB_DELTA + bj * HALF + 4)) * coef;
;                         const f32x4 o0 = g0 * acc[ai][bj][m][0], o1 = g1 * acc[ai][bj][m][1];
;                         u32x4 w; w.x = cvt_pk_bf16(o0[0], o0[1]); w.y = cvt_pk_bf16(o0[2], o0[3]); w.z = cvt_pk_bf16(o1[0], o1[1]); w.w = cvt_pk_bf16(o1[2], o1[3]);
;                         *(u32x4*)(op + bj * HALF) = w;
;                     }
;                     if (m & 1) asm volatile("" ::: "memory");
	v_pk_add_f32 v[24:25], v[236:237], v[240:241]
	v_pk_add_f32 v[22:23], v[234:235], v[238:239]
	v_pk_mul_f32 v[24:25], v[24:25], 0.5 op_sel_hi:[1,0]
	v_pk_add_f32 v[20:21], v[232:233], v[244:245]
	v_pk_add_f32 v[18:19], v[230:231], v[242:243]
	v_pk_mul_f32 v[20:21], v[20:21], 0.5 op_sel_hi:[1,0]
	v_pk_mul_f32 v[18:19], v[18:19], 0.5 op_sel_hi:[1,0]
	v_pk_mul_f32 v[22:23], v[22:23], 0.5 op_sel_hi:[1,0]
	v_pk_mul_f32 v[26:27], v[128:129], v[20:21]
	v_pk_mul_f32 v[20:21], v[126:127], v[18:19]
	v_pk_mul_f32 v[24:25], v[136:137], v[24:25]
	v_pk_mul_f32 v[22:23], v[134:135], v[22:23]
	v_lshl_add_u64 v[30:31], v[178:179], 0, s[16:17]
	v_cvt_pk_bf16_f32 v18, v22, v23
	v_cvt_pk_bf16_f32 v19, v24, v25
	v_cvt_pk_bf16_f32 v20, v20, v21
	v_cvt_pk_bf16_f32 v21, v26, v27
	global_store_dwordx4 v[174:175], v[18:21], off offset:256
	v_addc_co_u32_e32 v181, vcc, 0, v179, vcc
	global_load_dwordx4 v[18:21], v[178:179], off offset:16
	global_load_dwordx4 v[22:25], v[178:179], off
	global_load_dwordx4 v[26:29], v[180:181], off
	v_lshlrev_b64 v[174:175], 12, v[176:177]
	global_load_dwordx4 v[30:33], v[30:31], off offset:16
	global_load_dwordx4 v[230:233], v[178:179], off offset:528
	global_load_dwordx4 v[234:237], v[178:179], off offset:512
	global_load_dwordx4 v[238:241], v[180:181], off offset:512
	v_lshl_add_u64 v[246:247], v[178:179], 0, s[18:19]
	s_nop 0
	global_load_dwordx4 v[242:245], v[246:247], off offset:16
	v_lshl_add_u64 v[174:175], s[30:31], 0, v[174:175]
	v_lshl_add_u64 v[174:175], v[174:175], 0, v[12:13]
	v_add_u32_e32 v176, 0xffffe030, v10
	v_lshrrev_b32_e32 v3, 2, v176
	v_add_u32_e32 v3, 4, v3
	v_cmp_gt_i32_e32 vcc, s57, v2
	v_ashrrev_i32_e32 v177, 31, v176
	s_waitcnt vmcnt(4)
	v_pk_add_f32 v[24:25], v[24:25], v[28:29]
	v_pk_add_f32 v[22:23], v[22:23], v[26:27]
	v_pk_add_f32 v[20:21], v[20:21], v[32:33]
	v_pk_add_f32 v[18:19], v[18:19], v[30:31]
	v_pk_mul_f32 v[20:21], v[20:21], 0.5 op_sel_hi:[1,0]
	v_pk_mul_f32 v[18:19], v[18:19], 0.5 op_sel_hi:[1,0]
	v_pk_mul_f32 v[24:25], v[24:25], 0.5 op_sel_hi:[1,0]
	v_pk_mul_f32 v[22:23], v[22:23], 0.5 op_sel_hi:[1,0]
	v_pk_mul_f32 v[26:27], v[124:125], v[20:21]
	v_pk_mul_f32 v[20:21], v[122:123], v[18:19]
	v_pk_mul_f32 v[24:25], v[132:133], v[24:25]
	v_pk_mul_f32 v[22:23], v[130:131], v[22:23]
	v_lshl_add_u64 v[30:31], v[178:179], 0, s[18:19]
	v_cvt_pk_bf16_f32 v18, v22, v23
	v_cvt_pk_bf16_f32 v19, v24, v25
	v_cvt_pk_bf16_f32 v20, v20, v21
	v_cvt_pk_bf16_f32 v21, v26, v27
	global_store_dwordx4 v[174:175], v[18:21], off
	v_cndmask_b32_e32 v3, v3, v5, vcc
	v_mad_i64_i32 v[178:179], s[34:35], v3, s56, v[14:15]
	v_lshl_add_u64 v[178:179], v[178:179], 0, v[16:17]
	v_add_co_u32_e32 v180, vcc, s65, v178
	s_ashr_i32 s34, s38, 11
	s_nop 0
	v_addc_co_u32_e32 v181, vcc, 0, v179, vcc
	v_mov_b32_e32 v5, s34
	v_cmp_gt_i32_e32 vcc, s66, v10
	s_nop 1
	s_waitcnt vmcnt(1)
	v_pk_add_f32 v[24:25], v[236:237], v[240:241]
	v_pk_add_f32 v[22:23], v[234:235], v[238:239]
	v_pk_add_f32 v[20:21], v[232:233], v[244:245]
	v_pk_add_f32 v[18:19], v[230:231], v[242:243]
	v_pk_mul_f32 v[20:21], v[20:21], 0.5 op_sel_hi:[1,0]
	v_pk_mul_f32 v[18:19], v[18:19], 0.5 op_sel_hi:[1,0]
	v_pk_mul_f32 v[24:25], v[24:25], 0.5 op_sel_hi:[1,0]
	v_pk_mul_f32 v[22:23], v[22:23], 0.5 op_sel_hi:[1,0]
	v_pk_mul_f32 v[26:27], v[112:113], v[20:21]
	v_pk_mul_f32 v[20:21], v[110:111], v[18:19]
	v_pk_mul_f32 v[24:25], v[116:117], v[24:25]
	v_pk_mul_f32 v[22:23], v[114:115], v[22:23]
	v_lshl_add_u64 v[30:31], v[178:179], 0, s[16:17]
	v_cvt_pk_bf16_f32 v18, v22, v23
	v_cvt_pk_bf16_f32 v19, v24, v25
	v_cvt_pk_bf16_f32 v20, v20, v21
	v_cvt_pk_bf16_f32 v21, v26, v27
	global_store_dwordx4 v[174:175], v[18:21], off offset:256
	global_load_dwordx4 v[18:21], v[178:179], off offset:16
	s_nop 0
	global_load_dwordx4 v[22:25], v[178:179], off
	global_load_dwordx4 v[26:29], v[180:181], off
	v_lshlrev_b64 v[174:175], 12, v[176:177]
	global_load_dwordx4 v[30:33], v[30:31], off offset:16
	global_load_dwordx4 v[230:233], v[178:179], off offset:528
	global_load_dwordx4 v[234:237], v[178:179], off offset:512
	global_load_dwordx4 v[238:241], v[180:181], off offset:512
	v_lshl_add_u64 v[246:247], v[178:179], 0, s[18:19]
	s_nop 0
	global_load_dwordx4 v[242:245], v[246:247], off offset:16
	v_lshl_add_u64 v[174:175], s[30:31], 0, v[174:175]
	v_lshl_add_u64 v[174:175], v[174:175], 0, v[12:13]
	v_add_u32_e32 v176, 0xffffe080, v10
	v_lshrrev_b32_e32 v3, 2, v176
	v_or_b32_e32 v3, 4, v3
	v_cndmask_b32_e32 v3, v3, v5, vcc
	v_ashrrev_i32_e32 v177, 31, v176
	s_waitcnt vmcnt(4)
	v_pk_add_f32 v[24:25], v[24:25], v[28:29]
	v_pk_add_f32 v[22:23], v[22:23], v[26:27]
	v_pk_add_f32 v[20:21], v[20:21], v[32:33]
	v_pk_add_f32 v[18:19], v[18:19], v[30:31]
	v_pk_mul_f32 v[20:21], v[20:21], 0.5 op_sel_hi:[1,0]
	v_pk_mul_f32 v[18:19], v[18:19], 0.5 op_sel_hi:[1,0]
	v_pk_mul_f32 v[24:25], v[24:25], 0.5 op_sel_hi:[1,0]
	v_pk_mul_f32 v[22:23], v[22:23], 0.5 op_sel_hi:[1,0]
	v_pk_mul_f32 v[26:27], v[108:109], v[20:21]
	v_pk_mul_f32 v[20:21], v[106:107], v[18:19]
	v_pk_mul_f32 v[24:25], v[120:121], v[24:25]
	v_pk_mul_f32 v[22:23], v[118:119], v[22:23]
	v_lshl_add_u64 v[30:31], v[178:179], 0, s[18:19]
	v_cvt_pk_bf16_f32 v18, v22, v23
	v_cvt_pk_bf16_f32 v19, v24, v25
	v_cvt_pk_bf16_f32 v20, v20, v21
	v_cvt_pk_bf16_f32 v21, v26, v27
	global_store_dwordx4 v[174:175], v[18:21], off
	v_mad_i64_i32 v[178:179], s[34:35], v3, s56, v[14:15]
	v_lshl_add_u64 v[178:179], v[178:179], 0, v[16:17]
	v_add_co_u32_e32 v180, vcc, s65, v178
	s_nop 1
	s_waitcnt vmcnt(1)
; __device__ __forceinline__ unsigned cvt_pk_bf16(float lo, float hi) { unsigned r; asm volatile("v_cvt_pk_bf16_f32 %0, %1, %2" : "=v"(r) : "v"(lo), "v"(hi)); return r; }
;     __device__ __forceinline__ void operator()(const f32x4 (&acc)[2][2][4][2], const Unit& u, int wr, int wc, int fr, int fq) const {
;     ...
;                     const int row = row0 + ai * HALF + m * 16;
;                     const float* gp = gate + (size_t)modrow_of(row) * NMOD + col0;
;                     bf16_t* op = (bf16_t*)((char*)X + SLAB_MINUS_X) + ((size_t)u.kp * MS + (row - MP)) * DM + col0;
; #pragma unroll
;                     for (int bj = 0; bj < 2; ++bj) {
;                         const f32x4 g0 = (*(const f32x4*)(gp + bj * HALF) + *(const f32x4*)(gp + MODSB_DELTA + bj * HALF)) * coef, g1 = (*(const f32x4*)(gp + bj * HALF + 4) + *(const f32x4*)(gp + MODSB_DELTA + bj * HALF + 4)) * coef;
;                         const f32x4 o0 = g0 * acc[ai][bj][m][0], o1 = g1 * acc[ai][bj][m][1];
;                         u32x4 w; w.x = cvt_pk_bf16(o0[0], o0[1]); w.y = cvt_pk_bf16(o0[2], o0[3]); w.z = cvt_pk_bf16(o1[0], o1[1]); w.w = cvt_pk_bf16(o1[2], o1[3]);
;                         *(u32x4*)(op + bj * HALF) = w;
;                     }
;                     if (m & 1) asm volatile("" ::: "memory");
	v_pk_add_f32 v[24:25], v[236:237], v[240:241]
	v_pk_add_f32 v[22:23], v[234:235], v[238:239]
	v_pk_mul_f32 v[24:25], v[24:25], 0.5 op_sel_hi:[1,0]
	v_pk_add_f32 v[20:21], v[232:233], v[244:245]
	v_pk_add_f32 v[18:19], v[230:231], v[242:243]
	v_pk_mul_f32 v[20:21], v[20:21], 0.5 op_sel_hi:[1,0]
	v_pk_mul_f32 v[18:19], v[18:19], 0.5 op_sel_hi:[1,0]
	v_pk_mul_f32 v[22:23], v[22:23], 0.5 op_sel_hi:[1,0]
	v_pk_mul_f32 v[26:27], v[100:101], v[20:21]
	v_pk_mul_f32 v[20:21], v[98:99], v[18:19]
	v_pk_mul_f32 v[24:25], v[104:105], v[24:25]
	v_pk_mul_f32 v[22:23], v[102:103], v[22:23]
	v_lshl_add_u64 v[30:31], v[178:179], 0, s[16:17]
	v_cvt_pk_bf16_f32 v18, v22, v23
	v_cvt_pk_bf16_f32 v19, v24, v25
	v_cvt_pk_bf16_f32 v20, v20, v21
	v_cvt_pk_bf16_f32 v21, v26, v27
	global_store_dwordx4 v[174:175], v[18:21], off offset:256
	v_addc_co_u32_e32 v181, vcc, 0, v179, vcc
	global_load_dwordx4 v[18:21], v[178:179], off offset:16
	global_load_dwordx4 v[22:25], v[178:179], off
	global_load_dwordx4 v[26:29], v[180:181], off
	v_lshlrev_b64 v[174:175], 12, v[176:177]
	global_load_dwordx4 v[30:33], v[30:31], off offset:16
	global_load_dwordx4 v[230:233], v[178:179], off offset:528
	global_load_dwordx4 v[234:237], v[178:179], off offset:512
	global_load_dwordx4 v[238:241], v[180:181], off offset:512
	v_lshl_add_u64 v[246:247], v[178:179], 0, s[18:19]
	s_nop 0
	global_load_dwordx4 v[242:245], v[246:247], off offset:16
	v_lshl_add_u64 v[174:175], s[30:31], 0, v[174:175]
	v_lshl_add_u64 v[174:175], v[174:175], 0, v[12:13]
	v_add_u32_e32 v176, 0xffffe090, v10
	v_lshrrev_b32_e32 v3, 2, v176
	v_add_u32_e32 v3, 4, v3
	v_cmp_gt_i32_e32 vcc, s67, v10
	v_ashrrev_i32_e32 v177, 31, v176
	s_waitcnt vmcnt(4)
	v_pk_add_f32 v[24:25], v[24:25], v[28:29]
	v_pk_add_f32 v[22:23], v[22:23], v[26:27]
	v_pk_add_f32 v[20:21], v[20:21], v[32:33]
	v_pk_add_f32 v[18:19], v[18:19], v[30:31]
	v_pk_mul_f32 v[20:21], v[20:21], 0.5 op_sel_hi:[1,0]
	v_pk_mul_f32 v[18:19], v[18:19], 0.5 op_sel_hi:[1,0]
	v_pk_mul_f32 v[24:25], v[24:25], 0.5 op_sel_hi:[1,0]
	v_pk_mul_f32 v[22:23], v[22:23], 0.5 op_sel_hi:[1,0]
	v_pk_mul_f32 v[26:27], v[92:93], v[20:21]
	v_pk_mul_f32 v[20:21], v[90:91], v[18:19]
	v_pk_mul_f32 v[24:25], v[96:97], v[24:25]
	v_pk_mul_f32 v[22:23], v[94:95], v[22:23]
	v_lshl_add_u64 v[30:31], v[178:179], 0, s[18:19]
	v_cvt_pk_bf16_f32 v18, v22, v23
	v_cvt_pk_bf16_f32 v19, v24, v25
	v_cvt_pk_bf16_f32 v20, v20, v21
	v_cvt_pk_bf16_f32 v21, v26, v27
	global_store_dwordx4 v[174:175], v[18:21], off
	v_cndmask_b32_e32 v3, v3, v5, vcc
	v_mad_i64_i32 v[178:179], s[34:35], v3, s56, v[14:15]
	v_lshl_add_u64 v[178:179], v[178:179], 0, v[16:17]
	v_add_co_u32_e32 v180, vcc, s65, v178
	s_nop 1
	s_waitcnt vmcnt(1)
	v_pk_add_f32 v[24:25], v[236:237], v[240:241]
	v_pk_add_f32 v[22:23], v[234:235], v[238:239]
	v_pk_add_f32 v[20:21], v[232:233], v[244:245]
	v_pk_add_f32 v[18:19], v[230:231], v[242:243]
	v_pk_mul_f32 v[20:21], v[20:21], 0.5 op_sel_hi:[1,0]
	v_pk_mul_f32 v[18:19], v[18:19], 0.5 op_sel_hi:[1,0]
	v_pk_mul_f32 v[24:25], v[24:25], 0.5 op_sel_hi:[1,0]
	v_pk_mul_f32 v[22:23], v[22:23], 0.5 op_sel_hi:[1,0]
	v_pk_mul_f32 v[26:27], v[80:81], v[20:21]
	v_pk_mul_f32 v[20:21], v[78:79], v[18:19]
	v_pk_mul_f32 v[24:25], v[88:89], v[24:25]
	v_pk_mul_f32 v[22:23], v[86:87], v[22:23]
	v_lshl_add_u64 v[30:31], v[178:179], 0, s[16:17]
	v_cvt_pk_bf16_f32 v18, v22, v23
	v_cvt_pk_bf16_f32 v19, v24, v25
	v_cvt_pk_bf16_f32 v20, v20, v21
	v_cvt_pk_bf16_f32 v21, v26, v27
	global_store_dwordx4 v[174:175], v[18:21], off offset:256
	v_addc_co_u32_e32 v181, vcc, 0, v179, vcc
	global_load_dwordx4 v[18:21], v[178:179], off offset:16
	global_load_dwordx4 v[22:25], v[178:179], off
	global_load_dwordx4 v[26:29], v[180:181], off
	v_lshlrev_b64 v[174:175], 12, v[176:177]
	global_load_dwordx4 v[30:33], v[30:31], off offset:16
	global_load_dwordx4 v[230:233], v[178:179], off offset:528
	global_load_dwordx4 v[234:237], v[178:179], off offset:512
	global_load_dwordx4 v[238:241], v[180:181], off offset:512
	v_lshl_add_u64 v[246:247], v[178:179], 0, s[18:19]
	s_nop 0
	global_load_dwordx4 v[242:245], v[246:247], off offset:16
	v_lshl_add_u64 v[174:175], s[30:31], 0, v[174:175]
	v_lshl_add_u64 v[174:175], v[174:175], 0, v[12:13]
	v_add_u32_e32 v176, 0xffffe0a0, v10
	v_lshrrev_b32_e32 v3, 2, v176
	v_or_b32_e32 v3, 4, v3
	v_cmp_gt_i32_e32 vcc, s68, v10
	v_ashrrev_i32_e32 v177, 31, v176
	s_waitcnt vmcnt(4)
	v_pk_add_f32 v[24:25], v[24:25], v[28:29]
	v_pk_add_f32 v[22:23], v[22:23], v[26:27]
	v_pk_add_f32 v[20:21], v[20:21], v[32:33]
	v_pk_add_f32 v[18:19], v[18:19], v[30:31]
	v_pk_mul_f32 v[20:21], v[20:21], 0.5 op_sel_hi:[1,0]
	v_pk_mul_f32 v[18:19], v[18:19], 0.5 op_sel_hi:[1,0]
	v_pk_mul_f32 v[24:25], v[24:25], 0.5 op_sel_hi:[1,0]
	v_pk_mul_f32 v[22:23], v[22:23], 0.5 op_sel_hi:[1,0]
	v_pk_mul_f32 v[26:27], v[76:77], v[20:21]
	v_pk_mul_f32 v[20:21], v[74:75], v[18:19]
	v_pk_mul_f32 v[24:25], v[84:85], v[24:25]
	v_pk_mul_f32 v[22:23], v[82:83], v[22:23]
	v_lshl_add_u64 v[30:31], v[178:179], 0, s[18:19]
	v_cvt_pk_bf16_f32 v18, v22, v23
	v_cvt_pk_bf16_f32 v19, v24, v25
	v_cvt_pk_bf16_f32 v20, v20, v21
	v_cvt_pk_bf16_f32 v21, v26, v27
	global_store_dwordx4 v[174:175], v[18:21], off
	v_cndmask_b32_e32 v3, v3, v5, vcc
	v_mad_i64_i32 v[178:179], s[34:35], v3, s56, v[14:15]
	v_lshl_add_u64 v[178:179], v[178:179], 0, v[16:17]
	v_add_co_u32_e32 v180, vcc, s65, v178
	s_nop 1
	s_waitcnt vmcnt(1)
; __device__ __forceinline__ unsigned cvt_pk_bf16(float lo, float hi) { unsigned r; asm volatile("v_cvt_pk_bf16_f32 %0, %1, %2" : "=v"(r) : "v"(lo), "v"(hi)); return r; }
;     __device__ __forceinline__ void operator()(const f32x4 (&acc)[2][2][4][2], const Unit& u, int wr, int wc, int fr, int fq) const {
;     ...
;                     const int row = row0 + ai * HALF + m * 16;
;                     const float* gp = gate + (size_t)modrow_of(row) * NMOD + col0;
;                     bf16_t* op = (bf16_t*)((char*)X + SLAB_MINUS_X) + ((size_t)u.kp * MS + (row - MP)) * DM + col0;
; #pragma unroll
;                     for (int bj = 0; bj < 2; ++bj) {
;                         const f32x4 g0 = (*(const f32x4*)(gp + bj * HALF) + *(const f32x4*)(gp + MODSB_DELTA + bj * HALF)) * coef, g1 = (*(const f32x4*)(gp + bj * HALF + 4) + *(const f32x4*)(gp + MODSB_DELTA + bj * HALF + 4)) * coef;
;                         const f32x4 o0 = g0 * acc[ai][bj][m][0], o1 = g1 * acc[ai][bj][m][1];
;                         u32x4 w; w.x = cvt_pk_bf16(o0[0], o0[1]); w.y = cvt_pk_bf16(o0[2], o0[3]); w.z = cvt_pk_bf16(o1[0], o1[1]); w.w = cvt_pk_bf16(o1[2], o1[3]);
;                         *(u32x4*)(op + bj * HALF) = w;
;                     }
;                     if (m & 1) asm volatile("" ::: "memory");
;                 }
	v_pk_add_f32 v[24:25], v[236:237], v[240:241]
	v_pk_add_f32 v[22:23], v[234:235], v[238:239]
	v_pk_add_f32 v[20:21], v[232:233], v[244:245]
	v_pk_add_f32 v[18:19], v[230:231], v[242:243]
	v_pk_mul_f32 v[20:21], v[20:21], 0.5 op_sel_hi:[1,0]
	v_pk_mul_f32 v[18:19], v[18:19], 0.5 op_sel_hi:[1,0]
	v_pk_mul_f32 v[24:25], v[24:25], 0.5 op_sel_hi:[1,0]
	v_pk_mul_f32 v[22:23], v[22:23], 0.5 op_sel_hi:[1,0]
	v_pk_mul_f32 v[26:27], v[64:65], v[20:21]
	v_pk_mul_f32 v[20:21], v[62:63], v[18:19]
	v_pk_mul_f32 v[24:25], v[72:73], v[24:25]
	v_pk_mul_f32 v[22:23], v[70:71], v[22:23]
	v_lshl_add_u64 v[30:31], v[178:179], 0, s[16:17]
	v_cvt_pk_bf16_f32 v18, v22, v23
	v_cvt_pk_bf16_f32 v19, v24, v25
	v_cvt_pk_bf16_f32 v20, v20, v21
	v_cvt_pk_bf16_f32 v21, v26, v27
	global_store_dwordx4 v[174:175], v[18:21], off offset:256
	v_addc_co_u32_e32 v181, vcc, 0, v179, vcc
	global_load_dwordx4 v[18:21], v[178:179], off offset:16
	global_load_dwordx4 v[22:25], v[178:179], off
	global_load_dwordx4 v[26:29], v[180:181], off
	v_lshlrev_b64 v[174:175], 12, v[176:177]
	global_load_dwordx4 v[30:33], v[30:31], off offset:16
	global_load_dwordx4 v[230:233], v[178:179], off offset:528
	global_load_dwordx4 v[234:237], v[178:179], off offset:512
	global_load_dwordx4 v[238:241], v[180:181], off offset:512
	v_lshl_add_u64 v[246:247], v[178:179], 0, s[18:19]
	s_nop 0
	global_load_dwordx4 v[242:245], v[246:247], off offset:16
	v_lshl_add_u64 v[174:175], s[30:31], 0, v[174:175]
	v_lshl_add_u64 v[174:175], v[174:175], 0, v[12:13]
	v_add_u32_e32 v176, 0xffffe0b0, v10
	v_lshrrev_b32_e32 v3, 2, v176
	v_add_u32_e32 v3, 4, v3
	v_cmp_gt_i32_e32 vcc, s69, v10
	v_ashrrev_i32_e32 v177, 31, v176
	s_waitcnt vmcnt(4)
	v_pk_add_f32 v[24:25], v[24:25], v[28:29]
	v_pk_add_f32 v[22:23], v[22:23], v[26:27]
	v_pk_add_f32 v[20:21], v[20:21], v[32:33]
	v_pk_add_f32 v[18:19], v[18:19], v[30:31]
	v_pk_mul_f32 v[20:21], v[20:21], 0.5 op_sel_hi:[1,0]
	v_pk_mul_f32 v[18:19], v[18:19], 0.5 op_sel_hi:[1,0]
	v_pk_mul_f32 v[24:25], v[24:25], 0.5 op_sel_hi:[1,0]
	v_pk_mul_f32 v[22:23], v[22:23], 0.5 op_sel_hi:[1,0]
	v_pk_mul_f32 v[26:27], v[60:61], v[20:21]
	v_pk_mul_f32 v[20:21], v[58:59], v[18:19]
	v_pk_mul_f32 v[24:25], v[68:69], v[24:25]
	v_pk_mul_f32 v[22:23], v[66:67], v[22:23]
	v_lshl_add_u64 v[30:31], v[178:179], 0, s[18:19]
	v_cvt_pk_bf16_f32 v18, v22, v23
	v_cvt_pk_bf16_f32 v19, v24, v25
	v_cvt_pk_bf16_f32 v20, v20, v21
	v_cvt_pk_bf16_f32 v21, v26, v27
	global_store_dwordx4 v[174:175], v[18:21], off
	v_cndmask_b32_e32 v3, v3, v5, vcc
	v_mad_i64_i32 v[14:15], s[34:35], v3, s56, v[14:15]
	v_lshl_add_u64 v[178:179], v[14:15], 0, v[16:17]
	v_add_co_u32_e32 v180, vcc, s65, v178
	s_nop 1
	v_addc_co_u32_e32 v181, vcc, 0, v179, vcc
	s_nop 1
	s_waitcnt vmcnt(1)
	v_pk_add_f32 v[14:15], v[236:237], v[240:241]
	v_pk_add_f32 v[16:17], v[234:235], v[238:239]
	v_pk_add_f32 v[18:19], v[230:231], v[242:243]
	v_pk_add_f32 v[20:21], v[232:233], v[244:245]
	v_pk_mul_f32 v[14:15], v[14:15], 0.5 op_sel_hi:[1,0]
	v_pk_mul_f32 v[16:17], v[16:17], 0.5 op_sel_hi:[1,0]
	v_pk_mul_f32 v[18:19], v[18:19], 0.5 op_sel_hi:[1,0]
	v_pk_mul_f32 v[20:21], v[20:21], 0.5 op_sel_hi:[1,0]
	v_pk_mul_f32 v[22:23], v[56:57], v[14:15]
	v_pk_mul_f32 v[14:15], v[54:55], v[16:17]
	v_pk_mul_f32 v[16:17], v[46:47], v[18:19]
	v_pk_mul_f32 v[20:21], v[48:49], v[20:21]
	v_cvt_pk_bf16_f32 v14, v14, v15
	v_cvt_pk_bf16_f32 v15, v22, v23
	v_cvt_pk_bf16_f32 v16, v16, v17
	v_lshl_add_u64 v[26:27], v[178:179], 0, s[16:17]
	v_cvt_pk_bf16_f32 v17, v20, v21
	global_store_dwordx4 v[174:175], v[14:17], off offset:256
	global_load_dwordx4 v[14:17], v[178:179], off offset:16
	s_nop 0
	global_load_dwordx4 v[18:21], v[178:179], off
	global_load_dwordx4 v[22:25], v[180:181], off
	v_lshlrev_b64 v[30:31], 12, v[176:177]
	global_load_dwordx4 v[26:29], v[26:27], off offset:16
	global_load_dwordx4 v[230:233], v[178:179], off offset:528
	global_load_dwordx4 v[234:237], v[178:179], off offset:512
	global_load_dwordx4 v[238:241], v[180:181], off offset:512
	v_lshl_add_u64 v[246:247], v[178:179], 0, s[18:19]
	s_nop 0
	global_load_dwordx4 v[242:245], v[246:247], off offset:16
	v_lshl_add_u64 v[30:31], s[30:31], 0, v[30:31]
	v_lshl_add_u64 v[30:31], v[30:31], 0, v[12:13]
	s_waitcnt vmcnt(4)
	v_pk_add_f32 v[12:13], v[20:21], v[24:25]
	v_pk_add_f32 v[18:19], v[18:19], v[22:23]
	v_pk_add_f32 v[14:15], v[14:15], v[26:27]
	v_pk_add_f32 v[16:17], v[16:17], v[28:29]
	v_pk_mul_f32 v[12:13], v[12:13], 0.5 op_sel_hi:[1,0]
	v_pk_mul_f32 v[18:19], v[18:19], 0.5 op_sel_hi:[1,0]
	v_pk_mul_f32 v[14:15], v[14:15], 0.5 op_sel_hi:[1,0]
	v_pk_mul_f32 v[16:17], v[16:17], 0.5 op_sel_hi:[1,0]
	v_pk_mul_f32 v[20:21], v[52:53], v[12:13]
	v_pk_mul_f32 v[12:13], v[50:51], v[18:19]
	v_pk_mul_f32 v[14:15], v[42:43], v[14:15]
	v_pk_mul_f32 v[16:17], v[44:45], v[16:17]
	v_cvt_pk_bf16_f32 v12, v12, v13
	v_cvt_pk_bf16_f32 v13, v20, v21
	v_cvt_pk_bf16_f32 v14, v14, v15
	v_lshl_add_u64 v[24:25], v[178:179], 0, s[18:19]
	v_cvt_pk_bf16_f32 v15, v16, v17
	global_store_dwordx4 v[30:31], v[12:15], off
	s_waitcnt vmcnt(1)
	v_pk_add_f32 v[18:19], v[236:237], v[240:241]
	v_pk_add_f32 v[16:17], v[234:235], v[238:239]
	v_pk_mul_f32 v[18:19], v[18:19], 0.5 op_sel_hi:[1,0]
	v_pk_mul_f32 v[16:17], v[16:17], 0.5 op_sel_hi:[1,0]
	v_pk_mul_f32 v[18:19], v[40:41], v[18:19]
	v_pk_mul_f32 v[16:17], v[38:39], v[16:17]
	s_nop 1
	s_waitcnt vmcnt(1)
	v_pk_add_f32 v[14:15], v[232:233], v[244:245]
	v_pk_add_f32 v[12:13], v[230:231], v[242:243]
	v_pk_mul_f32 v[14:15], v[14:15], 0.5 op_sel_hi:[1,0]
	v_pk_mul_f32 v[12:13], v[12:13], 0.5 op_sel_hi:[1,0]
	v_pk_mul_f32 v[20:21], v[36:37], v[14:15]
	v_pk_mul_f32 v[14:15], v[34:35], v[12:13]
	v_cvt_pk_bf16_f32 v12, v16, v17
	v_cvt_pk_bf16_f32 v13, v18, v19
	s_nop 0
	v_cvt_pk_bf16_f32 v14, v14, v15
	v_cvt_pk_bf16_f32 v15, v20, v21
	global_store_dwordx4 v[30:31], v[12:15], off offset:256
	s_cbranch_execz .LBB0_1518
